# cache policy: nt on P0 x loads, P1 gate stores, P3 last-use gate loads, P4 x loads (+P0 wf batching, SP1 counted lgkmcnt)
# speedup vs baseline: 1.0172x; 1.0172x over previous
; #define GAS __attribute__((address_space(1)))
; template <bool IS_X>
; __device__ __forceinline__ void p0_rows(Frame& F, const float* srcb, const float* g, bf16* dstb, int nrows, const LAS float* wf, int gw, int NGW) {
;     const GAS f32x4* gr = (const GAS f32x4*)g + F.lane;
;     f32x4 wfr[4][4][2];
;     if (IS_X) {
; #pragma unroll
;         for (int j = 0; j < 4; ++j)
; #pragma unroll
;             for (int e = 0; e < 4; ++e) { const LAS f32x4* wp = (const LAS f32x4*)(wf + (256 * j + 4 * F.lane + e) * 8); wfr[j][e][0] = wp[0]; wfr[j][e][1] = wp[1]; } }
;     f32x4 nx[4];
;     if (gw < nrows) { const GAS f32x4* xr = (const GAS f32x4*)(srcb + (size_t)gw * D) + F.lane;
; #pragma unroll
;         for (int j = 0; j < 4; ++j) nx[j] = IS_X ? xr[64 * j] : __builtin_nontemporal_load(xr + 64 * j);     }
;     for (int m = gw; m < nrows; m += NGW) {
;         f32x4 v[4]; float s = 0.f;
; #pragma unroll
;         for (int j = 0; j < 4; ++j) v[j] = nx[j];
;         if (m + NGW < nrows) { const GAS f32x4* xr = (const GAS f32x4*)(srcb + (size_t)(m + NGW) * D) + F.lane;
; #pragma unroll
;             for (int j = 0; j < 4; ++j) nx[j] = IS_X ? xr[64 * j] : __builtin_nontemporal_load(xr + 64 * j);     }
; #pragma unroll
;         for (int j = 0; j < 4; ++j) s += (v[j].x * v[j].x + v[j].y * v[j].y) + (v[j].z * v[j].z + v[j].w * v[j].w);
;         const float rstd = __builtin_amdgcn_rsqf(wave_sum(s) * (1.f / D) + EPS);
; #pragma unroll
;         for (int j = 0; j < 4; ++j) { const f32x4 gg = gr[64 * j]; v[j] = v[j] * rstd * gg; }
;         GAS unsigned long long* o8 = (GAS unsigned long long*)(dstb + (size_t)m * D) + F.lane;
; #pragma unroll
;         for (int j = 0; j < 4; ++j) o8[64 * j] = (unsigned long long)pk2(v[j].x, v[j].y) | ((unsigned long long)pk2(v[j].z, v[j].w) << 32);
;         if (IS_X) {
;             float fl[8];
; #pragma unroll
;             for (int c = 0; c < 8; ++c) fl[c] = 0.f;
; #pragma unroll
;             for (int j = 0; j < 4; ++j)
; #pragma unroll
;                 for (int e = 0; e < 4; ++e) { const float hv = v[j][e]; const f32x4 w0 = wfr[j][e][0], w1 = wfr[j][e][1];
;                     fl[0] += hv * w0.x; fl[1] += hv * w0.y; fl[2] += hv * w0.z; fl[3] += hv * w0.w; fl[4] += hv * w1.x; fl[5] += hv * w1.y; fl[6] += hv * w1.z; fl[7] += hv * w1.w; }
;             float mine = 0.f;
; #pragma unroll
.LBB0_88:
	v_mov_b32_e32 v163, 0
	s_cmpk_gt_i32 s0, 0x3fff
	v_lshlrev_b32_e32 v162, 4, v178
	s_waitcnt vmcnt(8)
	ds_write_b32 v199, v200 offset:0
	ds_write_b32 v199, v201 offset:2048
	ds_write_b32 v199, v202 offset:4096
	ds_write_b32 v199, v203 offset:6144
	ds_write_b32 v199, v204 offset:8192
	ds_write_b32 v199, v205 offset:10240
	ds_write_b32 v199, v206 offset:12288
	ds_write_b32 v199, v207 offset:14336
	ds_write_b32 v199, v208 offset:16384
	ds_write_b32 v199, v209 offset:18432
	ds_write_b32 v199, v210 offset:20480
	ds_write_b32 v199, v211 offset:22528
	ds_write_b32 v199, v212 offset:24576
	ds_write_b32 v199, v213 offset:26624
	ds_write_b32 v199, v214 offset:28672
	ds_write_b32 v199, v215 offset:30720
	s_waitcnt lgkmcnt(0)
	s_barrier
	s_cbranch_scc1 .LBB0_96
	v_readlane_b32 s4, v247, 2
	v_readlane_b32 s10, v247, 8
	v_readlane_b32 s11, v247, 9
	v_readlane_b32 s5, v247, 3
	v_readlane_b32 s6, v247, 4
	v_readlane_b32 s7, v247, 5
	v_readlane_b32 s8, v247, 6
	v_readlane_b32 s9, v247, 7
	s_mov_b64 s[78:79], s[10:11]
	s_ashr_i32 s1, s0, 31
	s_mov_b64 s[72:73], s[4:5]
	s_lshl_b64 s[2:3], s[0:1], 12
	v_lshl_add_u32 v1, v178, 7, 0
	s_add_u32 s2, s72, s2
	v_add_u32_e32 v126, 0x10800, v1
	s_addc_u32 s3, s73, s3
	ds_read_b128 v[2:5], v126 offset:24688
	ds_read_b128 v[6:9], v126 offset:24672
	ds_read_b128 v[10:13], v126 offset:24656
	ds_read_b128 v[14:17], v126 offset:24640
	ds_read_b128 v[18:21], v126 offset:24624
	ds_read_b128 v[22:25], v126 offset:24608
	ds_read_b128 v[26:29], v126 offset:24592
	ds_read_b128 v[30:33], v126 offset:24576
	ds_read_b128 v[34:37], v126 offset:16496
	ds_read_b128 v[38:41], v126 offset:16480
	ds_read_b128 v[42:45], v126 offset:16464
	ds_read_b128 v[46:49], v126 offset:16448
	ds_read_b128 v[50:53], v126 offset:16432
	ds_read_b128 v[54:57], v126 offset:16416
	ds_read_b128 v[58:61], v126 offset:16400
	ds_read_b128 v[62:65], v126 offset:16384
	global_load_dwordx4 v[146:149], v162, s[2:3] offset:3072 nt
	global_load_dwordx4 v[150:153], v162, s[2:3] offset:2048 nt
	global_load_dwordx4 v[154:157], v162, s[2:3] offset:1024 nt
	global_load_dwordx4 v[158:161], v162, s[2:3] nt
	v_mbcnt_lo_u32_b32 v1, -1, 0
	v_mbcnt_hi_u32_b32 v66, -1, v1
	v_and_b32_e32 v1, 64, v66
	v_add_u32_e32 v67, 64, v1
	v_xor_b32_e32 v1, 1, v66
	v_cmp_lt_i32_e32 vcc, v1, v67
	v_xor_b32_e32 v68, 2, v66
	v_readlane_b32 s14, v247, 12
	v_cndmask_b32_e32 v1, v66, v1, vcc
	v_cmp_lt_i32_e32 vcc, v68, v67
	v_readlane_b32 s15, v247, 13
	s_mov_b64 s[82:83], s[14:15]
	v_cndmask_b32_e32 v68, v66, v68, vcc
	v_lshlrev_b32_e32 v179, 2, v68
	v_xor_b32_e32 v68, 4, v66
	v_cmp_lt_i32_e32 vcc, v68, v67
	s_lshl_b64 s[2:3], s[0:1], 5
	s_add_i32 s28, s0, s24
	v_cndmask_b32_e32 v68, v66, v68, vcc
	v_lshlrev_b32_e32 v180, 2, v68
	v_xor_b32_e32 v68, 8, v66
	v_cmp_lt_i32_e32 vcc, v68, v67
	s_ashr_i32 s25, s24, 31
	s_lshl_b64 s[26:27], s[0:1], 11
	v_cndmask_b32_e32 v68, v66, v68, vcc
	v_lshlrev_b32_e32 v181, 2, v68
	v_xor_b32_e32 v68, 16, v66
	v_cmp_lt_i32_e32 vcc, v68, v67
	s_ashr_i32 s29, s28, 31
	v_lshl_or_b32 v170, v178, 3, s26
	v_cndmask_b32_e32 v68, v66, v68, vcc
	v_lshlrev_b32_e32 v182, 2, v68
	v_xor_b32_e32 v68, 32, v66
	v_cmp_lt_i32_e32 vcc, v68, v67
	v_mov_b32_e32 v67, v163
	v_mov_b32_e32 v171, s27
	v_cndmask_b32_e32 v66, v66, v68, vcc
	v_lshlrev_b32_e32 v183, 2, v66
	v_lshlrev_b32_e32 v66, 2, v178
	v_lshl_add_u64 v[166:167], s[82:83], 0, v[66:67]
	v_lshl_add_u64 v[66:67], s[2:3], 0, v[66:67]
	s_mov_b64 s[2:3], 0x100000
	v_lshl_add_u64 v[168:169], v[66:67], 0, s[2:3]
	s_lshl_b64 s[2:3], s[24:25], 5
	s_lshl_b64 s[26:27], s[24:25], 11
	s_lshl_b64 s[28:29], s[28:29], 12
	s_add_u32 s28, s72, s28
	s_addc_u32 s29, s73, s29
	v_lshl_add_u64 v[66:67], s[28:29], 0, v[162:163]
	s_mov_b64 s[28:29], 0x800
	v_lshl_add_u64 v[172:173], v[66:67], 0, s[28:29]
	ds_read_b128 v[66:69], v126 offset:8304
	ds_read_b128 v[70:73], v126 offset:8288
	ds_read_b128 v[74:77], v126 offset:8272
	ds_read_b128 v[78:81], v126 offset:8256
	ds_read_b128 v[82:85], v126 offset:8240
	ds_read_b128 v[86:89], v126 offset:8224
	ds_read_b128 v[90:93], v126 offset:8208
	ds_read_b128 v[94:97], v126 offset:8192
	ds_read_b128 v[98:101], v126 offset:112
	ds_read_b128 v[102:105], v126 offset:96
	ds_read_b128 v[106:109], v126 offset:80
	ds_read_b128 v[110:113], v126 offset:64
	ds_read_b128 v[114:117], v126
	ds_read_b128 v[118:121], v126 offset:16
	ds_read_b128 v[122:125], v126 offset:32
	ds_read_b128 v[126:129], v126 offset:48
	v_readlane_b32 s12, v247, 10
	v_readlane_b32 s13, v247, 11
	v_readlane_b32 s16, v247, 14
	v_readlane_b32 s17, v247, 15
	v_readlane_b32 s18, v247, 16
	v_readlane_b32 s19, v247, 17
	s_mov_b64 s[76:77], s[8:9]
	s_mov_b64 s[74:75], s[6:7]
	v_lshl_add_u64 v[164:165], s[76:77], 0, v[162:163]
	v_lshlrev_b32_e32 v1, 2, v1
	v_cmp_gt_u32_e64 s[20:21], 8, v178
	v_cmp_eq_u32_e64 s[4:5], 7, v178
	v_cmp_eq_u32_e64 s[6:7], 6, v178
	v_cmp_eq_u32_e64 s[8:9], 5, v178
	v_cmp_eq_u32_e64 s[10:11], 4, v178
	v_cmp_eq_u32_e64 s[12:13], 3, v178
	v_cmp_eq_u32_e64 s[14:15], 2, v178
	v_cmp_eq_u32_e64 s[16:17], 1, v178
	v_cmp_eq_u32_e64 s[18:19], 0, v178
	s_lshl_b64 s[28:29], s[24:25], 12
	v_mov_b32_e32 v163, 0x358637bd
	s_movk_i32 s1, 0x7fff
	s_mov_b32 s25, 0xffff0000
	s_waitcnt vmcnt(3)
	v_mov_b64_e32 v[130:131], v[146:147]
	s_waitcnt vmcnt(2)
	v_mov_b64_e32 v[134:135], v[150:151]
	s_waitcnt vmcnt(1)
	v_mov_b64_e32 v[138:139], v[154:155]
	s_waitcnt vmcnt(0)
	v_mov_b64_e32 v[142:143], v[158:159]
	s_mov_b32 s33, 0x2c00000
	s_mov_b32 s36, 0xbfb8aa3b
	s_mov_b32 s37, 0xb2a5705f
	s_mov_b32 s38, 0x42ce8ed0
	s_mov_b32 s39, 0xc2b17218
	s_mov_b32 s40, 0x7f800000
	s_mov_b32 s41, 0x3f2aaaab
	v_mov_b32_e32 v184, 0x3ecc95a3
	s_mov_b32 s42, 0x3f317218
	s_mov_b32 s43, 0x33800000
	v_mov_b32_e32 v185, 0x7f800000
	v_mov_b32_e32 v174, 0x3f317218
	s_mov_b32 s44, s0
	v_mov_b64_e32 v[132:133], v[148:149]
	v_mov_b64_e32 v[136:137], v[152:153]
	v_mov_b64_e32 v[140:141], v[156:157]
	v_mov_b64_e32 v[144:145], v[160:161]
	s_branch .LBB0_91

; #define GAS __attribute__((address_space(1)))
; template <bool IS_X>
; __device__ __forceinline__ void p0_rows(Frame& F, const float* srcb, const float* g, bf16* dstb, int nrows, const LAS float* wf, int gw, int NGW) {
;     ...
;     for (int m = gw; m < nrows; m += NGW) {
;         f32x4 v[4]; float s = 0.f;
; #pragma unroll
;         for (int j = 0; j < 4; ++j) v[j] = nx[j];
;         if (m + NGW < nrows) { const GAS f32x4* xr = (const GAS f32x4*)(srcb + (size_t)(m + NGW) * D) + F.lane;
; #pragma unroll
;             for (int j = 0; j < 4; ++j) nx[j] = IS_X ? xr[64 * j] : __builtin_nontemporal_load(xr + 64 * j);     }
.LBB0_91:
	s_add_i32 s44, s44, s24
	s_cmpk_gt_i32 s44, 0x3fff
	s_cselect_b64 s[30:31], -1, 0
	s_and_b64 vcc, exec, s[30:31]
	s_cbranch_vccnz .LBB0_93
	global_load_dwordx4 v[142:145], v[172:173], off offset:-2048 nt
	global_load_dwordx4 v[138:141], v[172:173], off offset:-1024 nt
	global_load_dwordx4 v[134:137], v[172:173], off nt
	global_load_dwordx4 v[130:133], v[172:173], off offset:1024 nt

; __device__ __forceinline__ u32x4 pack8(const f32x4 a, const f32x4 b) { u32x4 w; w.x = cvt_pk_bf16(a[0], a[1]); w.y = cvt_pk_bf16(a[2], a[3]); w.z = cvt_pk_bf16(b[0], b[1]); w.w = cvt_pk_bf16(b[2], b[3]); return w; }
; __device__ __forceinline__ float sigm(float x) { return __builtin_amdgcn_rcpf(1.0f + __builtin_amdgcn_exp2f(x)); }
;     __device__ __forceinline__ void run(const acc_t& acc, const Unit& u, int wr, int wc, int fr, int fq, const int A0, const int A1) const {
;     ...
;         } else if (pn < 26) {
;             const int g = (pn - 14) >> 2; bf16_t* G = g < 2 ? G0 + (size_t)g * M * D : G2;
;             bf16_t* base = G + (size_t)row0 * D + ((pn - 14) & 3) * 256 + wc * 64 + 8 * fq;
; #pragma unroll
;             for (int ai = A0; ai < A1; ++ai)
; #pragma unroll
;                 for (int m = 0; m < 4; ++m) { bf16_t* rowp = base + (size_t)(ai * HALF + m * 16) * D;
; #pragma unroll
;                     for (int bj = 0; bj < 2; ++bj) { f32x4 a = acc[ai][bj][m][0], b = acc[ai][bj][m][1];
; #pragma unroll
;                         for (int e = 0; e < 4; ++e) { a[e] = sigm(a[e]); b[e] = sigm(b[e]); }
;                         *(u32x4*)(rowp + 32 * bj) = pack8(a, b); } }
.LBB0_196:
	s_andn2_b64 vcc, exec, s[30:31]
	s_cbranch_vccnz .LBB0_198
	s_add_i32 s8, s6, -14
	s_lshl_b32 s13, s8, 23
	v_readlane_b32 s72, v247, 57
	s_and_b32 s13, s13, 0x2000000
	v_readlane_b32 s76, v247, 61
	v_readlane_b32 s77, v247, 62
	s_add_u32 s13, s76, s13
	s_addc_u32 s21, s77, 0
	v_exp_f32_e32 v187, v71
	s_cmp_lt_u32 s8, 8
	v_ashrrev_i32_e32 v171, 31, v170
	s_cselect_b32 s31, s21, s84
	s_cselect_b32 s30, s13, s47
	v_lshlrev_b64 v[172:173], 11, v[170:171]
	s_lshl_b32 s8, s8, 9
	v_lshl_add_u64 v[172:173], s[30:31], 0, v[172:173]
	s_and_b32 s8, s8, 0x600
	v_lshl_add_u64 v[172:173], v[172:173], 0, s[8:9]
	s_lshl_b32 s8, s37, 1
	v_add_f32_e32 v187, 1.0, v187
	v_lshl_add_u64 v[172:173], v[172:173], 0, s[8:9]
	v_lshlrev_b32_e32 v164, 1, v162
	v_rcp_f32_e32 v189, v187
	v_exp_f32_e32 v187, v72
	v_exp_f32_e32 v171, v66
	v_lshl_add_u64 v[172:173], v[172:173], 0, v[164:165]
	v_exp_f32_e32 v164, v70
	v_exp_f32_e32 v186, v67
	v_exp_f32_e32 v188, v68
	v_exp_f32_e32 v190, v69
	v_exp_f32_e32 v191, v73
	v_add_f32_e32 v187, 1.0, v187
	v_add_f32_e32 v171, 1.0, v171
	v_add_f32_e32 v164, 1.0, v164
	v_add_f32_e32 v186, 1.0, v186
	v_add_f32_e32 v188, 1.0, v188
	v_rcp_f32_e32 v192, v187
	v_add_f32_e32 v187, 1.0, v190
	v_add_f32_e32 v190, 1.0, v191
	v_rcp_f32_e32 v171, v171
	v_rcp_f32_e32 v164, v164
	v_rcp_f32_e32 v186, v186
	v_rcp_f32_e32 v188, v188
	v_rcp_f32_e32 v187, v187
	v_rcp_f32_e32 v190, v190
	v_cvt_pk_bf16_f32 v186, v171, v186
	v_exp_f32_e32 v171, v102
	v_cvt_pk_bf16_f32 v187, v188, v187
	v_cvt_pk_bf16_f32 v188, v164, v189
	v_cvt_pk_bf16_f32 v189, v192, v190
	global_store_dwordx4 v[172:173], v[186:189], off nt
	v_exp_f32_e32 v164, v98
	v_exp_f32_e32 v190, v101
	v_exp_f32_e32 v187, v103
	v_exp_f32_e32 v186, v99
	v_exp_f32_e32 v188, v100
	v_exp_f32_e32 v191, v105
	v_add_f32_e32 v187, 1.0, v187
	v_rcp_f32_e32 v189, v187
	v_exp_f32_e32 v187, v104
	v_add_f32_e32 v164, 1.0, v164
	v_add_f32_e32 v171, 1.0, v171
	v_add_f32_e32 v186, 1.0, v186
	v_add_f32_e32 v187, 1.0, v187
	v_add_f32_e32 v188, 1.0, v188
	v_rcp_f32_e32 v192, v187
	v_add_f32_e32 v187, 1.0, v190
	v_add_f32_e32 v190, 1.0, v191
	v_rcp_f32_e32 v164, v164
	v_rcp_f32_e32 v171, v171
	v_rcp_f32_e32 v186, v186
	v_rcp_f32_e32 v188, v188
	v_rcp_f32_e32 v187, v187
	v_rcp_f32_e32 v190, v190
	v_cvt_pk_bf16_f32 v186, v164, v186
	v_exp_f32_e32 v191, v81
	v_cvt_pk_bf16_f32 v187, v188, v187
	v_cvt_pk_bf16_f32 v188, v171, v189
	v_cvt_pk_bf16_f32 v189, v192, v190
	global_store_dwordx4 v[172:173], v[186:189], off offset:64 nt
	v_exp_f32_e32 v171, v78
	v_exp_f32_e32 v190, v77
	v_exp_f32_e32 v187, v79
	v_exp_f32_e32 v188, v76
	v_exp_f32_e32 v164, v74
	v_exp_f32_e32 v186, v75
	v_add_f32_e32 v187, 1.0, v187
	v_rcp_f32_e32 v189, v187
	v_exp_f32_e32 v187, v80
	v_add_f32_e32 v171, 1.0, v171
	v_add_f32_e32 v188, 1.0, v188
	v_add_f32_e32 v164, 1.0, v164
	v_add_f32_e32 v187, 1.0, v187
	v_rcp_f32_e32 v192, v187
	v_add_f32_e32 v187, 1.0, v190
	v_add_f32_e32 v190, 1.0, v191
	v_rcp_f32_e32 v171, v171
	v_add_f32_e32 v186, 1.0, v186
	v_rcp_f32_e32 v188, v188
	v_rcp_f32_e32 v187, v187
	v_rcp_f32_e32 v190, v190
	v_rcp_f32_e32 v164, v164
	v_rcp_f32_e32 v186, v186
	v_cvt_pk_bf16_f32 v187, v188, v187
	v_cvt_pk_bf16_f32 v188, v171, v189
	v_cvt_pk_bf16_f32 v189, v192, v190
	v_add_co_u32_e32 v190, vcc, s55, v172
	v_cvt_pk_bf16_f32 v186, v164, v186
	s_nop 0
	v_addc_co_u32_e32 v191, vcc, 0, v173, vcc
	global_store_dwordx4 v[190:191], v[186:189], off nt
	v_exp_f32_e32 v164, v106
	v_exp_f32_e32 v171, v110
	v_exp_f32_e32 v187, v111
	v_exp_f32_e32 v186, v107
	v_exp_f32_e32 v188, v108
	v_exp_f32_e32 v192, v109
	v_add_f32_e32 v187, 1.0, v187
	v_rcp_f32_e32 v189, v187
	v_exp_f32_e32 v187, v112
	v_exp_f32_e32 v193, v113
	v_add_f32_e32 v164, 1.0, v164
	v_add_f32_e32 v171, 1.0, v171
	v_add_f32_e32 v187, 1.0, v187
	v_add_f32_e32 v186, 1.0, v186
	v_add_f32_e32 v188, 1.0, v188
	v_rcp_f32_e32 v194, v187
	v_add_f32_e32 v187, 1.0, v192
	v_add_f32_e32 v192, 1.0, v193
	v_rcp_f32_e32 v164, v164
	v_rcp_f32_e32 v171, v171
	v_rcp_f32_e32 v186, v186
	v_rcp_f32_e32 v188, v188
	v_rcp_f32_e32 v187, v187
; __device__ __forceinline__ u32x4 pack8(const f32x4 a, const f32x4 b) { u32x4 w; w.x = cvt_pk_bf16(a[0], a[1]); w.y = cvt_pk_bf16(a[2], a[3]); w.z = cvt_pk_bf16(b[0], b[1]); w.w = cvt_pk_bf16(b[2], b[3]); return w; }
; __device__ __forceinline__ float sigm(float x) { return __builtin_amdgcn_rcpf(1.0f + __builtin_amdgcn_exp2f(x)); }
;     __device__ __forceinline__ void run(const acc_t& acc, const Unit& u, int wr, int wc, int fr, int fq, const int A0, const int A1) const {
;     ...
;         } else if (pn < 26) {
;             const int g = (pn - 14) >> 2; bf16_t* G = g < 2 ? G0 + (size_t)g * M * D : G2;
;             bf16_t* base = G + (size_t)row0 * D + ((pn - 14) & 3) * 256 + wc * 64 + 8 * fq;
; #pragma unroll
;             for (int ai = A0; ai < A1; ++ai)
; #pragma unroll
;                 for (int m = 0; m < 4; ++m) { bf16_t* rowp = base + (size_t)(ai * HALF + m * 16) * D;
; #pragma unroll
;                     for (int bj = 0; bj < 2; ++bj) { f32x4 a = acc[ai][bj][m][0], b = acc[ai][bj][m][1];
; #pragma unroll
;                         for (int e = 0; e < 4; ++e) { a[e] = sigm(a[e]); b[e] = sigm(b[e]); }
;                         *(u32x4*)(rowp + 32 * bj) = pack8(a, b); } }
	v_rcp_f32_e32 v192, v192
	v_cvt_pk_bf16_f32 v186, v164, v186
	v_exp_f32_e32 v164, v82
	v_cvt_pk_bf16_f32 v187, v188, v187
	v_cvt_pk_bf16_f32 v188, v171, v189
	v_cvt_pk_bf16_f32 v189, v194, v192
	global_store_dwordx4 v[190:191], v[186:189], off offset:64 nt
	v_exp_f32_e32 v171, v86
	v_exp_f32_e32 v190, v85
	v_exp_f32_e32 v187, v87
	v_exp_f32_e32 v188, v84
	v_exp_f32_e32 v191, v89
	v_exp_f32_e32 v186, v83
	v_add_f32_e32 v187, 1.0, v187
	v_rcp_f32_e32 v189, v187
	v_exp_f32_e32 v187, v88
	v_add_f32_e32 v171, 1.0, v171
	v_add_f32_e32 v188, 1.0, v188
	v_add_f32_e32 v164, 1.0, v164
	v_add_f32_e32 v187, 1.0, v187
	v_rcp_f32_e32 v192, v187
	v_add_f32_e32 v187, 1.0, v190
	v_add_f32_e32 v190, 1.0, v191
	v_rcp_f32_e32 v171, v171
	v_add_f32_e32 v186, 1.0, v186
	v_rcp_f32_e32 v188, v188
	v_rcp_f32_e32 v187, v187
	v_rcp_f32_e32 v190, v190
	v_rcp_f32_e32 v164, v164
	v_rcp_f32_e32 v186, v186
	s_mov_b32 s8, 0x10000
	v_cvt_pk_bf16_f32 v187, v188, v187
	v_cvt_pk_bf16_f32 v188, v171, v189
	v_cvt_pk_bf16_f32 v189, v192, v190
	v_add_co_u32_e32 v190, vcc, s8, v172
	v_cvt_pk_bf16_f32 v186, v164, v186
	s_nop 0
	v_addc_co_u32_e32 v191, vcc, 0, v173, vcc
	global_store_dwordx4 v[190:191], v[186:189], off nt
	v_exp_f32_e32 v164, v114
	v_exp_f32_e32 v171, v118
	v_exp_f32_e32 v187, v119
	v_exp_f32_e32 v186, v115
	v_exp_f32_e32 v188, v116
	v_exp_f32_e32 v192, v117
	v_add_f32_e32 v187, 1.0, v187
	v_rcp_f32_e32 v189, v187
	v_exp_f32_e32 v187, v120
	v_exp_f32_e32 v193, v121
	v_add_f32_e32 v164, 1.0, v164
	v_add_f32_e32 v171, 1.0, v171
	v_add_f32_e32 v187, 1.0, v187
	v_add_f32_e32 v186, 1.0, v186
	v_add_f32_e32 v188, 1.0, v188
	v_rcp_f32_e32 v194, v187
	v_add_f32_e32 v187, 1.0, v192
	v_add_f32_e32 v192, 1.0, v193
	v_rcp_f32_e32 v164, v164
	v_rcp_f32_e32 v171, v171
	v_rcp_f32_e32 v186, v186
	v_rcp_f32_e32 v188, v188
	v_rcp_f32_e32 v187, v187
	v_rcp_f32_e32 v192, v192
	v_cvt_pk_bf16_f32 v186, v164, v186
	v_exp_f32_e32 v164, v90
	v_cvt_pk_bf16_f32 v187, v188, v187
	v_cvt_pk_bf16_f32 v188, v171, v189
	v_cvt_pk_bf16_f32 v189, v194, v192
	global_store_dwordx4 v[190:191], v[186:189], off offset:64 nt
	v_exp_f32_e32 v171, v94
	v_exp_f32_e32 v190, v93
	v_exp_f32_e32 v187, v95
	v_exp_f32_e32 v186, v91
	v_exp_f32_e32 v188, v92
	v_exp_f32_e32 v191, v97
	v_add_f32_e32 v187, 1.0, v187
	v_rcp_f32_e32 v189, v187
	v_exp_f32_e32 v187, v96
	v_add_f32_e32 v164, 1.0, v164
	v_add_f32_e32 v171, 1.0, v171
	v_add_f32_e32 v186, 1.0, v186
	v_add_f32_e32 v187, 1.0, v187
	v_add_f32_e32 v188, 1.0, v188
	v_rcp_f32_e32 v192, v187
	v_add_f32_e32 v187, 1.0, v190
	v_add_f32_e32 v190, 1.0, v191
	v_rcp_f32_e32 v164, v164
	v_rcp_f32_e32 v171, v171
	v_rcp_f32_e32 v186, v186
	v_rcp_f32_e32 v188, v188
	v_rcp_f32_e32 v187, v187
	v_rcp_f32_e32 v190, v190
	s_mov_b32 s8, 0x18000
	v_add_co_u32_e32 v172, vcc, s8, v172
	v_cvt_pk_bf16_f32 v186, v164, v186
	v_cvt_pk_bf16_f32 v187, v188, v187
	v_cvt_pk_bf16_f32 v188, v171, v189
	v_cvt_pk_bf16_f32 v189, v192, v190
	v_addc_co_u32_e32 v173, vcc, 0, v173, vcc
	global_store_dwordx4 v[172:173], v[186:189], off nt
	v_exp_f32_e32 v164, v122
	v_exp_f32_e32 v171, v126
	v_exp_f32_e32 v187, v127
	v_exp_f32_e32 v186, v123
	v_exp_f32_e32 v188, v124
	v_exp_f32_e32 v190, v125
	v_add_f32_e32 v187, 1.0, v187
	v_rcp_f32_e32 v189, v187
	v_exp_f32_e32 v187, v128
	v_exp_f32_e32 v191, v129
	v_add_f32_e32 v164, 1.0, v164
	v_add_f32_e32 v171, 1.0, v171
	v_add_f32_e32 v187, 1.0, v187
	v_add_f32_e32 v186, 1.0, v186
	v_add_f32_e32 v188, 1.0, v188
	v_rcp_f32_e32 v192, v187
	v_add_f32_e32 v187, 1.0, v190
	v_add_f32_e32 v190, 1.0, v191
	v_rcp_f32_e32 v164, v164
	v_rcp_f32_e32 v171, v171
	v_rcp_f32_e32 v186, v186
	v_rcp_f32_e32 v188, v188
	v_rcp_f32_e32 v187, v187
	v_rcp_f32_e32 v190, v190
	v_cvt_pk_bf16_f32 v186, v164, v186
	v_readlane_b32 s73, v247, 58
	v_cvt_pk_bf16_f32 v187, v188, v187
	v_cvt_pk_bf16_f32 v188, v171, v189
	v_cvt_pk_bf16_f32 v189, v192, v190
	v_readlane_b32 s74, v247, 59
	v_readlane_b32 s75, v247, 60
	v_readlane_b32 s78, v247, 63
	v_readlane_b32 s79, v246, 0
	global_store_dwordx4 v[172:173], v[186:189], off offset:64 nt

; __device__ __forceinline__ u32x4 pack8(const f32x4 a, const f32x4 b) { u32x4 w; w.x = cvt_pk_bf16(a[0], a[1]); w.y = cvt_pk_bf16(a[2], a[3]); w.z = cvt_pk_bf16(b[0], b[1]); w.w = cvt_pk_bf16(b[2], b[3]); return w; }
; __device__ __forceinline__ float sigm(float x) { return __builtin_amdgcn_rcpf(1.0f + __builtin_amdgcn_exp2f(x)); }
;     __device__ __forceinline__ void run(const acc_t& acc, const Unit& u, int wr, int wc, int fr, int fq, const int A0, const int A1) const {
;     ...
;         } else if (pn < 26) {
;             const int g = (pn - 14) >> 2; bf16_t* G = g < 2 ? G0 + (size_t)g * M * D : G2;
;             bf16_t* base = G + (size_t)row0 * D + ((pn - 14) & 3) * 256 + wc * 64 + 8 * fq;
; #pragma unroll
;             for (int ai = A0; ai < A1; ++ai)
; #pragma unroll
;                 for (int m = 0; m < 4; ++m) { bf16_t* rowp = base + (size_t)(ai * HALF + m * 16) * D;
; #pragma unroll
;                     for (int bj = 0; bj < 2; ++bj) { f32x4 a = acc[ai][bj][m][0], b = acc[ai][bj][m][1];
; #pragma unroll
;                         for (int e = 0; e < 4; ++e) { a[e] = sigm(a[e]); b[e] = sigm(b[e]); }
;                         *(u32x4*)(rowp + 32 * bj) = pack8(a, b); } }
.LBB0_216:
	s_andn2_b64 vcc, exec, s[2:3]
	s_cbranch_vccnz .LBB0_218
	v_exp_f32_e32 v69, v58
	s_add_i32 s7, s6, -14
	s_lshl_b32 s2, s7, 23
	v_readlane_b32 s24, v247, 57
	v_add_f32_e32 v69, 1.0, v69
	v_rcp_f32_e32 v71, v69
	v_exp_f32_e32 v69, v59
	s_and_b32 s2, s2, 0x2000000
	v_readlane_b32 s28, v247, 61
	v_readlane_b32 s29, v247, 62
	v_add_f32_e32 v69, 1.0, v69
	v_rcp_f32_e32 v73, v69
	v_exp_f32_e32 v69, v60
	s_add_u32 s2, s28, s2
	v_exp_f32_e32 v72, v64
	v_exp_f32_e32 v74, v65
	s_addc_u32 s3, s29, 0
	v_exp_f32_e32 v68, v62
	v_exp_f32_e32 v70, v63
	v_exp_f32_e32 v75, v61
	s_cmp_lt_u32 s7, 8
	v_ashrrev_i32_e32 v171, 31, v170
	s_cselect_b32 s3, s3, s84
	s_cselect_b32 s2, s2, s47
	v_lshlrev_b64 v[66:67], 11, v[170:171]
	v_add_f32_e32 v69, 1.0, v69
	v_lshl_add_u64 v[66:67], s[2:3], 0, v[66:67]
	s_lshl_b32 s2, s7, 9
	v_add_f32_e32 v72, 1.0, v72
	v_rcp_f32_e32 v76, v69
	v_add_f32_e32 v69, 1.0, v74
	s_and_b32 s8, s2, 0x600
	v_add_f32_e32 v68, 1.0, v68
	v_add_f32_e32 v70, 1.0, v70
	v_rcp_f32_e32 v72, v72
	v_rcp_f32_e32 v69, v69
	v_add_f32_e32 v74, 1.0, v75
	v_lshl_add_u64 v[66:67], v[66:67], 0, s[8:9]
	s_lshl_b32 s8, s37, 1
	v_rcp_f32_e32 v68, v68
	v_rcp_f32_e32 v70, v70
	v_rcp_f32_e32 v74, v74
	v_lshl_add_u64 v[66:67], v[66:67], 0, s[8:9]
	v_lshlrev_b32_e32 v164, 1, v162
	v_lshl_add_u64 v[66:67], v[66:67], 0, v[164:165]
	s_mov_b32 s2, 0x40000
	v_cvt_pk_bf16_f32 v69, v72, v69
	v_add_co_u32_e32 v72, vcc, s2, v66
	v_cvt_pk_bf16_f32 v68, v68, v70
	v_cvt_pk_bf16_f32 v70, v71, v73
	v_cvt_pk_bf16_f32 v71, v76, v74
	v_addc_co_u32_e32 v73, vcc, 0, v67, vcc
	global_store_dwordx4 v[72:73], v[68:71], off nt
	v_exp_f32_e32 v74, v54
	v_exp_f32_e32 v76, v57
	v_exp_f32_e32 v68, v50
	v_exp_f32_e32 v70, v55
	v_add_f32_e32 v69, 1.0, v74
	v_exp_f32_e32 v74, v56
	v_add_f32_e32 v68, 1.0, v68
	v_rcp_f32_e32 v71, v68
	v_exp_f32_e32 v68, v51
	v_exp_f32_e32 v77, v53
	v_add_f32_e32 v70, 1.0, v70
	v_add_f32_e32 v74, 1.0, v74
	v_add_f32_e32 v68, 1.0, v68
	v_rcp_f32_e32 v75, v68
	v_exp_f32_e32 v68, v52
	v_rcp_f32_e32 v69, v69
	v_rcp_f32_e32 v70, v70
	v_rcp_f32_e32 v74, v74
	v_add_f32_e32 v68, 1.0, v68
	v_rcp_f32_e32 v78, v68
	v_add_f32_e32 v68, 1.0, v76
	v_rcp_f32_e32 v76, v68
	v_add_f32_e32 v68, 1.0, v77
	v_rcp_f32_e32 v77, v68
	v_cvt_pk_bf16_f32 v68, v69, v70
	v_cvt_pk_bf16_f32 v69, v74, v76
	v_cvt_pk_bf16_f32 v70, v71, v75
	v_cvt_pk_bf16_f32 v71, v78, v77
	global_store_dwordx4 v[72:73], v[68:71], off offset:64 nt
	v_exp_f32_e32 v74, v46
	v_exp_f32_e32 v72, v48
	v_exp_f32_e32 v68, v42
	v_exp_f32_e32 v70, v47
	v_add_f32_e32 v69, 1.0, v74
	v_exp_f32_e32 v74, v49
	v_add_f32_e32 v68, 1.0, v68
	v_rcp_f32_e32 v71, v68
	v_exp_f32_e32 v68, v43
	v_exp_f32_e32 v75, v45
	v_add_f32_e32 v70, 1.0, v70
	v_add_f32_e32 v72, 1.0, v72
	v_add_f32_e32 v68, 1.0, v68
	v_rcp_f32_e32 v73, v68
	v_exp_f32_e32 v68, v44
	v_rcp_f32_e32 v69, v69
	v_rcp_f32_e32 v70, v70
	v_rcp_f32_e32 v72, v72
	v_add_f32_e32 v68, 1.0, v68
	v_rcp_f32_e32 v76, v68
	v_add_f32_e32 v68, 1.0, v74
	v_rcp_f32_e32 v74, v68
	v_add_f32_e32 v68, 1.0, v75
	v_rcp_f32_e32 v75, v68
	s_mov_b32 s2, 0x48000
	v_cvt_pk_bf16_f32 v68, v69, v70
	v_cvt_pk_bf16_f32 v69, v72, v74
	v_add_co_u32_e32 v72, vcc, s2, v66
	v_cvt_pk_bf16_f32 v70, v71, v73
	v_cvt_pk_bf16_f32 v71, v76, v75
	v_addc_co_u32_e32 v73, vcc, 0, v67, vcc
	global_store_dwordx4 v[72:73], v[68:71], off nt
	v_exp_f32_e32 v74, v38
	v_exp_f32_e32 v76, v41
	v_exp_f32_e32 v68, v34
	v_exp_f32_e32 v70, v39
	v_add_f32_e32 v69, 1.0, v74
	v_exp_f32_e32 v74, v40
	v_add_f32_e32 v68, 1.0, v68
	v_rcp_f32_e32 v71, v68
	v_exp_f32_e32 v68, v35
	v_exp_f32_e32 v77, v37
	v_add_f32_e32 v70, 1.0, v70
	v_add_f32_e32 v74, 1.0, v74
	v_add_f32_e32 v68, 1.0, v68
	v_rcp_f32_e32 v75, v68
	v_exp_f32_e32 v68, v36
	v_rcp_f32_e32 v69, v69
	v_rcp_f32_e32 v70, v70
	v_rcp_f32_e32 v74, v74
	v_add_f32_e32 v68, 1.0, v68
	v_rcp_f32_e32 v78, v68
; __device__ __forceinline__ u32x4 pack8(const f32x4 a, const f32x4 b) { u32x4 w; w.x = cvt_pk_bf16(a[0], a[1]); w.y = cvt_pk_bf16(a[2], a[3]); w.z = cvt_pk_bf16(b[0], b[1]); w.w = cvt_pk_bf16(b[2], b[3]); return w; }
; __device__ __forceinline__ float sigm(float x) { return __builtin_amdgcn_rcpf(1.0f + __builtin_amdgcn_exp2f(x)); }
;     __device__ __forceinline__ void run(const acc_t& acc, const Unit& u, int wr, int wc, int fr, int fq, const int A0, const int A1) const {
;     ...
;         } else if (pn < 26) {
;             const int g = (pn - 14) >> 2; bf16_t* G = g < 2 ? G0 + (size_t)g * M * D : G2;
;             bf16_t* base = G + (size_t)row0 * D + ((pn - 14) & 3) * 256 + wc * 64 + 8 * fq;
; #pragma unroll
;             for (int ai = A0; ai < A1; ++ai)
; #pragma unroll
;                 for (int m = 0; m < 4; ++m) { bf16_t* rowp = base + (size_t)(ai * HALF + m * 16) * D;
; #pragma unroll
;                     for (int bj = 0; bj < 2; ++bj) { f32x4 a = acc[ai][bj][m][0], b = acc[ai][bj][m][1];
; #pragma unroll
;                         for (int e = 0; e < 4; ++e) { a[e] = sigm(a[e]); b[e] = sigm(b[e]); }
;                         *(u32x4*)(rowp + 32 * bj) = pack8(a, b); } }
	v_add_f32_e32 v68, 1.0, v76
	v_rcp_f32_e32 v76, v68
	v_add_f32_e32 v68, 1.0, v77
	v_rcp_f32_e32 v77, v68
	v_cvt_pk_bf16_f32 v68, v69, v70
	v_cvt_pk_bf16_f32 v69, v74, v76
	v_cvt_pk_bf16_f32 v70, v71, v75
	v_cvt_pk_bf16_f32 v71, v78, v77
	global_store_dwordx4 v[72:73], v[68:71], off offset:64 nt
	v_exp_f32_e32 v74, v30
	v_exp_f32_e32 v72, v32
	v_exp_f32_e32 v68, v26
	v_exp_f32_e32 v70, v31
	v_add_f32_e32 v69, 1.0, v74
	v_exp_f32_e32 v74, v33
	v_add_f32_e32 v68, 1.0, v68
	v_rcp_f32_e32 v71, v68
	v_exp_f32_e32 v68, v27
	v_exp_f32_e32 v75, v29
	v_add_f32_e32 v70, 1.0, v70
	v_add_f32_e32 v72, 1.0, v72
	v_add_f32_e32 v68, 1.0, v68
	v_rcp_f32_e32 v73, v68
	v_exp_f32_e32 v68, v28
	v_rcp_f32_e32 v69, v69
	v_rcp_f32_e32 v70, v70
	v_rcp_f32_e32 v72, v72
	v_add_f32_e32 v68, 1.0, v68
	v_rcp_f32_e32 v76, v68
	v_add_f32_e32 v68, 1.0, v74
	v_rcp_f32_e32 v74, v68
	v_add_f32_e32 v68, 1.0, v75
	v_rcp_f32_e32 v75, v68
	s_mov_b32 s2, 0x50000
	v_cvt_pk_bf16_f32 v68, v69, v70
	v_cvt_pk_bf16_f32 v69, v72, v74
	v_add_co_u32_e32 v72, vcc, s2, v66
	v_cvt_pk_bf16_f32 v70, v71, v73
	v_cvt_pk_bf16_f32 v71, v76, v75
	v_addc_co_u32_e32 v73, vcc, 0, v67, vcc
	global_store_dwordx4 v[72:73], v[68:71], off nt
	v_exp_f32_e32 v74, v22
	v_exp_f32_e32 v76, v25
	v_exp_f32_e32 v68, v18
	v_exp_f32_e32 v70, v23
	v_add_f32_e32 v69, 1.0, v74
	v_exp_f32_e32 v74, v24
	v_add_f32_e32 v68, 1.0, v68
	v_rcp_f32_e32 v71, v68
	v_exp_f32_e32 v68, v19
	v_exp_f32_e32 v77, v21
	v_add_f32_e32 v70, 1.0, v70
	v_add_f32_e32 v74, 1.0, v74
	v_add_f32_e32 v68, 1.0, v68
	v_rcp_f32_e32 v75, v68
	v_exp_f32_e32 v68, v20
	v_rcp_f32_e32 v69, v69
	v_rcp_f32_e32 v70, v70
	v_rcp_f32_e32 v74, v74
	v_add_f32_e32 v68, 1.0, v68
	v_rcp_f32_e32 v78, v68
	v_add_f32_e32 v68, 1.0, v76
	v_rcp_f32_e32 v76, v68
	v_add_f32_e32 v68, 1.0, v77
	v_rcp_f32_e32 v77, v68
	v_cvt_pk_bf16_f32 v68, v69, v70
	v_cvt_pk_bf16_f32 v69, v74, v76
	v_cvt_pk_bf16_f32 v70, v71, v75
	v_cvt_pk_bf16_f32 v71, v78, v77
	global_store_dwordx4 v[72:73], v[68:71], off offset:64 nt
	v_exp_f32_e32 v74, v14
	v_exp_f32_e32 v72, v16
	v_exp_f32_e32 v68, v10
	v_exp_f32_e32 v70, v15
	v_add_f32_e32 v69, 1.0, v74
	v_exp_f32_e32 v74, v17
	v_add_f32_e32 v68, 1.0, v68
	v_rcp_f32_e32 v71, v68
	v_exp_f32_e32 v68, v11
	v_add_f32_e32 v70, 1.0, v70
	v_add_f32_e32 v72, 1.0, v72
	v_exp_f32_e32 v75, v13
	v_add_f32_e32 v68, 1.0, v68
	v_rcp_f32_e32 v73, v68
	v_exp_f32_e32 v68, v12
	v_rcp_f32_e32 v69, v69
	v_rcp_f32_e32 v70, v70
	v_rcp_f32_e32 v72, v72
	v_add_f32_e32 v68, 1.0, v68
	v_rcp_f32_e32 v76, v68
	v_add_f32_e32 v68, 1.0, v74
	v_rcp_f32_e32 v74, v68
	v_add_f32_e32 v68, 1.0, v75
	s_mov_b32 s2, 0x58000
	v_rcp_f32_e32 v75, v68
	v_cvt_pk_bf16_f32 v68, v69, v70
	v_cvt_pk_bf16_f32 v69, v72, v74
	v_add_co_u32_e32 v72, vcc, s2, v66
	v_exp_f32_e32 v66, v2
	v_cvt_pk_bf16_f32 v70, v71, v73
	v_cvt_pk_bf16_f32 v71, v76, v75
	v_addc_co_u32_e32 v73, vcc, 0, v67, vcc
	v_add_f32_e32 v66, 1.0, v66
	global_store_dwordx4 v[72:73], v[68:71], off nt
	v_exp_f32_e32 v74, v6
	v_exp_f32_e32 v75, v5
	v_rcp_f32_e32 v69, v66
	v_exp_f32_e32 v66, v3
	v_add_f32_e32 v67, 1.0, v74
	v_exp_f32_e32 v74, v9
	v_exp_f32_e32 v68, v7
	v_add_f32_e32 v66, 1.0, v66
	v_rcp_f32_e32 v71, v66
	v_exp_f32_e32 v66, v4
	v_exp_f32_e32 v70, v8
	v_add_f32_e32 v68, 1.0, v68
	v_rcp_f32_e32 v67, v67
	v_add_f32_e32 v66, 1.0, v66
	v_rcp_f32_e32 v76, v66
	v_add_f32_e32 v66, 1.0, v74
	v_add_f32_e32 v70, 1.0, v70
	v_rcp_f32_e32 v74, v66
	v_add_f32_e32 v66, 1.0, v75
	v_rcp_f32_e32 v68, v68
	v_rcp_f32_e32 v70, v70
	v_rcp_f32_e32 v75, v66
	v_readlane_b32 s25, v247, 58
	v_cvt_pk_bf16_f32 v66, v67, v68
	v_cvt_pk_bf16_f32 v67, v70, v74
	v_cvt_pk_bf16_f32 v68, v69, v71
	v_cvt_pk_bf16_f32 v69, v76, v75
	v_readlane_b32 s26, v247, 59
	v_readlane_b32 s27, v247, 60
	v_readlane_b32 s30, v247, 63
	v_readlane_b32 s31, v246, 0
	global_store_dwordx4 v[72:73], v[66:69], off offset:64 nt

; __device__ __forceinline__ u32x4 pack8(const f32x4 a, const f32x4 b) { u32x4 w; w.x = cvt_pk_bf16(a[0], a[1]); w.y = cvt_pk_bf16(a[2], a[3]); w.z = cvt_pk_bf16(b[0], b[1]); w.w = cvt_pk_bf16(b[2], b[3]); return w; }
; __device__ __forceinline__ float sigm(float x) { return __builtin_amdgcn_rcpf(1.0f + __builtin_amdgcn_exp2f(x)); }
;     __device__ __forceinline__ void run(const acc_t& acc, const Unit& u, int wr, int wc, int fr, int fq, const int A0, const int A1) const {
;     ...
;         } else if (pn < 26) {
;             const int g = (pn - 14) >> 2; bf16_t* G = g < 2 ? G0 + (size_t)g * M * D : G2;
;             bf16_t* base = G + (size_t)row0 * D + ((pn - 14) & 3) * 256 + wc * 64 + 8 * fq;
; #pragma unroll
;             for (int ai = A0; ai < A1; ++ai)
; #pragma unroll
;                 for (int m = 0; m < 4; ++m) { bf16_t* rowp = base + (size_t)(ai * HALF + m * 16) * D;
; #pragma unroll
;                     for (int bj = 0; bj < 2; ++bj) { f32x4 a = acc[ai][bj][m][0], b = acc[ai][bj][m][1];
; #pragma unroll
;                         for (int e = 0; e < 4; ++e) { a[e] = sigm(a[e]); b[e] = sigm(b[e]); }
;                         *(u32x4*)(rowp + 32 * bj) = pack8(a, b); } }
.LBB0_238:
	s_andn2_b64 vcc, exec, s[2:3]
	s_cbranch_vccnz .LBB0_240
	s_add_i32 s2, s6, -14
	s_lshl_b32 s3, s2, 23
	s_and_b32 s4, s3, 0x2000000
	s_add_u32 s4, s60, s4
	s_addc_u32 s5, s61, 0
	s_cmp_lt_u32 s2, 8
	v_ashrrev_i32_e32 v67, 31, v66
	s_cselect_b32 s5, s5, s84
	s_cselect_b32 s4, s4, s47
	v_lshlrev_b64 v[68:69], 11, v[66:67]
	s_lshl_b32 s2, s2, 9
	s_mov_b32 s3, 0
	v_lshl_add_u64 v[68:69], s[4:5], 0, v[68:69]
	s_and_b32 s2, s2, 0x600
	v_lshl_add_u64 v[68:69], v[68:69], 0, s[2:3]
	s_lshl_b32 s2, s37, 1
	v_lshl_add_u64 v[68:69], v[68:69], 0, s[2:3]
	v_lshlrev_b32_e32 v70, 1, v162
	v_mov_b32_e32 v71, 0
	v_lshl_add_u64 v[68:69], v[68:69], 0, v[70:71]
	v_exp_f32_e32 v71, v59
	v_exp_f32_e32 v67, v58
	v_exp_f32_e32 v72, v64
	v_exp_f32_e32 v74, v65
	v_add_f32_e32 v71, 1.0, v71
	v_rcp_f32_e32 v73, v71
	v_exp_f32_e32 v71, v60
	v_exp_f32_e32 v75, v61
	v_exp_f32_e32 v1, v62
	v_exp_f32_e32 v70, v63
	v_add_f32_e32 v71, 1.0, v71
	v_add_f32_e32 v67, 1.0, v67
	v_add_f32_e32 v72, 1.0, v72
	v_rcp_f32_e32 v76, v71
	v_add_f32_e32 v71, 1.0, v74
	v_add_f32_e32 v74, 1.0, v75
	v_add_f32_e32 v1, 1.0, v1
	v_rcp_f32_e32 v67, v67
	v_add_f32_e32 v70, 1.0, v70
	v_rcp_f32_e32 v72, v72
	v_rcp_f32_e32 v71, v71
	v_rcp_f32_e32 v74, v74
	v_rcp_f32_e32 v1, v1
	v_rcp_f32_e32 v70, v70
	s_mov_b32 s2, 0x40000
	v_cvt_pk_bf16_f32 v71, v72, v71
	v_cvt_pk_bf16_f32 v72, v67, v73
	v_cvt_pk_bf16_f32 v73, v76, v74
	v_add_co_u32_e32 v74, vcc, s2, v68
	v_cvt_pk_bf16_f32 v70, v1, v70
	s_nop 0
	v_addc_co_u32_e32 v75, vcc, 0, v69, vcc
	global_store_dwordx4 v[74:75], v[70:73], off nt
	v_exp_f32_e32 v1, v54
	v_exp_f32_e32 v67, v50
	v_exp_f32_e32 v71, v51
	v_exp_f32_e32 v70, v55
	v_exp_f32_e32 v72, v56
	v_exp_f32_e32 v76, v57
	v_add_f32_e32 v71, 1.0, v71
	v_rcp_f32_e32 v73, v71
	v_exp_f32_e32 v71, v52
	v_exp_f32_e32 v77, v53
	v_add_f32_e32 v1, 1.0, v1
	v_add_f32_e32 v67, 1.0, v67
	v_add_f32_e32 v71, 1.0, v71
	v_add_f32_e32 v70, 1.0, v70
	v_add_f32_e32 v72, 1.0, v72
	v_rcp_f32_e32 v78, v71
	v_add_f32_e32 v71, 1.0, v76
	v_add_f32_e32 v76, 1.0, v77
	v_rcp_f32_e32 v1, v1
	v_rcp_f32_e32 v67, v67
	v_rcp_f32_e32 v70, v70
	v_rcp_f32_e32 v72, v72
	v_rcp_f32_e32 v71, v71
	v_rcp_f32_e32 v76, v76
	v_cvt_pk_bf16_f32 v70, v1, v70
	v_exp_f32_e32 v1, v46
	v_cvt_pk_bf16_f32 v71, v72, v71
	v_cvt_pk_bf16_f32 v72, v67, v73
	v_cvt_pk_bf16_f32 v73, v78, v76
	global_store_dwordx4 v[74:75], v[70:73], off offset:64 nt
	v_exp_f32_e32 v67, v42
	v_exp_f32_e32 v74, v49
	v_exp_f32_e32 v71, v43
	v_exp_f32_e32 v72, v48
	v_exp_f32_e32 v75, v45
	v_exp_f32_e32 v70, v47
	v_add_f32_e32 v71, 1.0, v71
	v_rcp_f32_e32 v73, v71
	v_exp_f32_e32 v71, v44
	v_add_f32_e32 v67, 1.0, v67
	v_add_f32_e32 v72, 1.0, v72
	v_add_f32_e32 v1, 1.0, v1
	v_add_f32_e32 v71, 1.0, v71
	v_rcp_f32_e32 v76, v71
	v_add_f32_e32 v71, 1.0, v74
	v_add_f32_e32 v74, 1.0, v75
	v_rcp_f32_e32 v67, v67
	v_add_f32_e32 v70, 1.0, v70
	v_rcp_f32_e32 v72, v72
	v_rcp_f32_e32 v71, v71
	v_rcp_f32_e32 v74, v74
	v_rcp_f32_e32 v1, v1
	v_rcp_f32_e32 v70, v70
	s_mov_b32 s2, 0x48000
	v_cvt_pk_bf16_f32 v71, v72, v71
	v_cvt_pk_bf16_f32 v72, v67, v73
	v_cvt_pk_bf16_f32 v73, v76, v74
	v_add_co_u32_e32 v74, vcc, s2, v68
	v_cvt_pk_bf16_f32 v70, v1, v70
	s_nop 0
	v_addc_co_u32_e32 v75, vcc, 0, v69, vcc
	global_store_dwordx4 v[74:75], v[70:73], off nt
	v_exp_f32_e32 v1, v38
	v_exp_f32_e32 v67, v34
	v_exp_f32_e32 v71, v35
	v_exp_f32_e32 v70, v39
	v_exp_f32_e32 v72, v40
	v_exp_f32_e32 v76, v41
	v_add_f32_e32 v71, 1.0, v71
	v_rcp_f32_e32 v73, v71
	v_exp_f32_e32 v71, v36
	v_exp_f32_e32 v77, v37
	v_add_f32_e32 v1, 1.0, v1
	v_add_f32_e32 v67, 1.0, v67
	v_add_f32_e32 v71, 1.0, v71
	v_add_f32_e32 v70, 1.0, v70
	v_add_f32_e32 v72, 1.0, v72
	v_rcp_f32_e32 v78, v71
	v_add_f32_e32 v71, 1.0, v76
	v_add_f32_e32 v76, 1.0, v77
; __device__ __forceinline__ u32x4 pack8(const f32x4 a, const f32x4 b) { u32x4 w; w.x = cvt_pk_bf16(a[0], a[1]); w.y = cvt_pk_bf16(a[2], a[3]); w.z = cvt_pk_bf16(b[0], b[1]); w.w = cvt_pk_bf16(b[2], b[3]); return w; }
; __device__ __forceinline__ float sigm(float x) { return __builtin_amdgcn_rcpf(1.0f + __builtin_amdgcn_exp2f(x)); }
;     __device__ __forceinline__ void run(const acc_t& acc, const Unit& u, int wr, int wc, int fr, int fq, const int A0, const int A1) const {
;     ...
;         } else if (pn < 26) {
;             const int g = (pn - 14) >> 2; bf16_t* G = g < 2 ? G0 + (size_t)g * M * D : G2;
;             bf16_t* base = G + (size_t)row0 * D + ((pn - 14) & 3) * 256 + wc * 64 + 8 * fq;
; #pragma unroll
;             for (int ai = A0; ai < A1; ++ai)
; #pragma unroll
;                 for (int m = 0; m < 4; ++m) { bf16_t* rowp = base + (size_t)(ai * HALF + m * 16) * D;
; #pragma unroll
;                     for (int bj = 0; bj < 2; ++bj) { f32x4 a = acc[ai][bj][m][0], b = acc[ai][bj][m][1];
; #pragma unroll
;                         for (int e = 0; e < 4; ++e) { a[e] = sigm(a[e]); b[e] = sigm(b[e]); }
;                         *(u32x4*)(rowp + 32 * bj) = pack8(a, b); } }
	v_rcp_f32_e32 v1, v1
	v_rcp_f32_e32 v67, v67
	v_rcp_f32_e32 v70, v70
	v_rcp_f32_e32 v72, v72
	v_rcp_f32_e32 v71, v71
	v_rcp_f32_e32 v76, v76
	v_cvt_pk_bf16_f32 v70, v1, v70
	v_exp_f32_e32 v1, v30
	v_cvt_pk_bf16_f32 v71, v72, v71
	v_cvt_pk_bf16_f32 v72, v67, v73
	v_cvt_pk_bf16_f32 v73, v78, v76
	global_store_dwordx4 v[74:75], v[70:73], off offset:64 nt
	v_exp_f32_e32 v67, v26
	v_exp_f32_e32 v74, v33
	v_exp_f32_e32 v71, v27
	v_exp_f32_e32 v72, v32
	v_exp_f32_e32 v75, v29
	v_exp_f32_e32 v70, v31
	v_add_f32_e32 v71, 1.0, v71
	v_rcp_f32_e32 v73, v71
	v_exp_f32_e32 v71, v28
	v_add_f32_e32 v67, 1.0, v67
	v_add_f32_e32 v72, 1.0, v72
	v_add_f32_e32 v1, 1.0, v1
	v_add_f32_e32 v71, 1.0, v71
	v_rcp_f32_e32 v76, v71
	v_add_f32_e32 v71, 1.0, v74
	v_add_f32_e32 v74, 1.0, v75
	v_rcp_f32_e32 v67, v67
	v_add_f32_e32 v70, 1.0, v70
	v_rcp_f32_e32 v72, v72
	v_rcp_f32_e32 v71, v71
	v_rcp_f32_e32 v74, v74
	v_rcp_f32_e32 v1, v1
	v_rcp_f32_e32 v70, v70
	s_mov_b32 s2, 0x50000
	v_cvt_pk_bf16_f32 v71, v72, v71
	v_cvt_pk_bf16_f32 v72, v67, v73
	v_cvt_pk_bf16_f32 v73, v76, v74
	v_add_co_u32_e32 v74, vcc, s2, v68
	v_cvt_pk_bf16_f32 v70, v1, v70
	s_nop 0
	v_addc_co_u32_e32 v75, vcc, 0, v69, vcc
	global_store_dwordx4 v[74:75], v[70:73], off nt
	v_exp_f32_e32 v1, v22
	v_exp_f32_e32 v67, v18
	v_exp_f32_e32 v71, v19
	v_exp_f32_e32 v70, v23
	v_exp_f32_e32 v72, v24
	v_exp_f32_e32 v76, v25
	v_add_f32_e32 v71, 1.0, v71
	v_rcp_f32_e32 v73, v71
	v_exp_f32_e32 v71, v20
	v_exp_f32_e32 v77, v21
	v_add_f32_e32 v1, 1.0, v1
	v_add_f32_e32 v67, 1.0, v67
	v_add_f32_e32 v71, 1.0, v71
	v_add_f32_e32 v70, 1.0, v70
	v_add_f32_e32 v72, 1.0, v72
	v_rcp_f32_e32 v78, v71
	v_add_f32_e32 v71, 1.0, v76
	v_add_f32_e32 v76, 1.0, v77
	v_rcp_f32_e32 v1, v1
	v_rcp_f32_e32 v67, v67
	v_rcp_f32_e32 v70, v70
	v_rcp_f32_e32 v72, v72
	v_rcp_f32_e32 v71, v71
	v_rcp_f32_e32 v76, v76
	v_cvt_pk_bf16_f32 v70, v1, v70
	v_exp_f32_e32 v1, v14
	v_cvt_pk_bf16_f32 v71, v72, v71
	v_cvt_pk_bf16_f32 v72, v67, v73
	v_cvt_pk_bf16_f32 v73, v78, v76
	global_store_dwordx4 v[74:75], v[70:73], off offset:64 nt
	v_exp_f32_e32 v67, v10
	v_exp_f32_e32 v74, v17
	v_exp_f32_e32 v71, v11
	v_exp_f32_e32 v72, v16
	v_exp_f32_e32 v75, v13
	v_add_f32_e32 v67, 1.0, v67
	v_add_f32_e32 v71, 1.0, v71
	v_rcp_f32_e32 v73, v71
	v_exp_f32_e32 v71, v12
	v_add_f32_e32 v72, 1.0, v72
	v_exp_f32_e32 v70, v15
	v_rcp_f32_e32 v67, v67
	v_add_f32_e32 v71, 1.0, v71
	v_rcp_f32_e32 v76, v71
	v_add_f32_e32 v71, 1.0, v74
	v_add_f32_e32 v74, 1.0, v75
	v_rcp_f32_e32 v72, v72
	v_rcp_f32_e32 v71, v71
	v_rcp_f32_e32 v74, v74
	s_mov_b32 s2, 0x58000
	v_add_f32_e32 v1, 1.0, v1
	v_add_f32_e32 v70, 1.0, v70
	v_cvt_pk_bf16_f32 v71, v72, v71
	v_cvt_pk_bf16_f32 v72, v67, v73
	v_cvt_pk_bf16_f32 v73, v76, v74
	v_add_co_u32_e32 v74, vcc, s2, v68
	v_rcp_f32_e32 v1, v1
	v_rcp_f32_e32 v70, v70
	v_addc_co_u32_e32 v75, vcc, 0, v69, vcc
	v_exp_f32_e32 v69, v3
	v_cvt_pk_bf16_f32 v70, v1, v70
	global_store_dwordx4 v[74:75], v[70:73], off nt
	v_exp_f32_e32 v1, v6
	v_add_f32_e32 v69, 1.0, v69
	v_rcp_f32_e32 v71, v69
	v_exp_f32_e32 v69, v4
	v_exp_f32_e32 v67, v2
	v_exp_f32_e32 v68, v7
	v_exp_f32_e32 v70, v8
	v_exp_f32_e32 v72, v9
	v_exp_f32_e32 v73, v5
	v_add_f32_e32 v69, 1.0, v69
	v_add_f32_e32 v1, 1.0, v1
	v_add_f32_e32 v67, 1.0, v67
	v_add_f32_e32 v68, 1.0, v68
	v_add_f32_e32 v70, 1.0, v70
	v_rcp_f32_e32 v76, v69
	v_add_f32_e32 v69, 1.0, v72
	v_add_f32_e32 v72, 1.0, v73
	v_rcp_f32_e32 v1, v1
	v_rcp_f32_e32 v67, v67
	v_rcp_f32_e32 v68, v68
	v_rcp_f32_e32 v70, v70
	v_rcp_f32_e32 v69, v69
	v_rcp_f32_e32 v72, v72
	v_cvt_pk_bf16_f32 v68, v1, v68
	v_cvt_pk_bf16_f32 v69, v70, v69
	v_cvt_pk_bf16_f32 v70, v67, v71
	v_cvt_pk_bf16_f32 v71, v76, v72
	global_store_dwordx4 v[74:75], v[68:71], off offset:64 nt

;     __device__ __forceinline__ void operator()(acc_t& acc, const Unit& u, int wr, int wc, int fr, int fq) const {
;         const int br = u.br; const size_t base = (size_t)(u.pm * BM + wr * 64 + fr) * D + u.pn * BM + wc * 32 + 8 * fq;
;         const bf16_t* Ga = (br < 2 ? G0 + (size_t)br * M * D : G2) + base;
;         const bf16_t* Gb = (br == 0 ? G0 + (size_t)M * D : G2) + base;
;         bf16_t* O = MRG + base;
; #pragma unroll
;         for (int ai = 0; ai < 2; ++ai) {
;             u32x4 ga[4][2], gb[4][2];
; #pragma unroll
;             for (int m = 0; m < 4; ++m)
; #pragma unroll
;                 for (int bj = 0; bj < 2; ++bj) { const size_t o = (size_t)(ai * HALF + m * 16) * D + HALF * bj; ga[m][bj] = *(const u32x4*)(Ga + o); if (br < 2) gb[m][bj] = *(const u32x4*)(Gb + o); }
.LBB0_581:
	v_lshl_add_u32 v130, s4, 8, v210
	s_lshl_b32 s2, s2, 8
	v_ashrrev_i32_e32 v131, 31, v130
	s_ashr_i32 s3, s2, 31
	v_lshlrev_b64 v[130:131], 10, v[130:131]
	s_cmp_gt_i32 s6, 1
	v_lshl_add_u64 v[196:197], v[130:131], 0, s[2:3]
	s_cselect_b64 s[2:3], -1, 0
	s_ashr_i32 s7, s6, 31
	s_lshl_b64 s[4:5], s[6:7], 25
	s_add_u32 s7, s60, s4
	s_addc_u32 s11, s61, s5
	s_cmp_lt_i32 s6, 2
	s_cselect_b64 s[20:21], -1, 0
	v_or_b32_e32 v196, v196, v194
	s_and_b64 s[4:5], s[20:21], exec
	s_cselect_b32 s5, s11, s84
	s_cselect_b32 s4, s7, s47
	v_lshlrev_b64 v[130:131], 1, v[196:197]
	v_lshl_add_u64 v[200:201], s[4:5], 0, v[130:131]
	global_load_dwordx4 v[190:193], v[200:201], off nt
	s_cmp_eq_u32 s6, 0
	s_cselect_b32 s5, s39, s84
	s_cselect_b32 s4, s38, s47
	v_lshl_add_u64 v[198:199], s[4:5], 0, v[130:131]
	s_and_b64 vcc, exec, s[2:3]
	s_cbranch_vccnz .LBB0_583
	global_load_dwordx4 v[158:161], v[198:199], off
.LBB0_583:
	global_load_dwordx4 v[186:189], v[200:201], off offset:256 nt
	v_cndmask_b32_e64 v130, 0, 1, s[20:21]
	v_cmp_ne_u32_e64 s[4:5], 1, v130
	s_andn2_b64 vcc, exec, s[20:21]
	s_cbranch_vccnz .LBB0_585
	global_load_dwordx4 v[154:157], v[198:199], off offset:256
.LBB0_585:
	v_add_co_u32_e32 v130, vcc, 0x8000, v200
	s_nop 1
	v_addc_co_u32_e32 v131, vcc, 0, v201, vcc
	global_load_dwordx4 v[182:185], v[130:131], off nt
	s_and_b64 vcc, exec, s[4:5]
	s_cbranch_vccnz .LBB0_587
	v_add_co_u32_e32 v130, vcc, 0x8000, v198
	s_nop 1
	v_addc_co_u32_e32 v131, vcc, 0, v199, vcc
	global_load_dwordx4 v[150:153], v[130:131], off
.LBB0_587:
	v_add_co_u32_e32 v130, vcc, 0x8000, v200
	s_nop 1
	v_addc_co_u32_e32 v131, vcc, 0, v201, vcc
	global_load_dwordx4 v[178:181], v[130:131], off offset:256 nt
	s_and_b64 vcc, exec, s[4:5]
	s_cbranch_vccnz .LBB0_589
	v_add_co_u32_e32 v130, vcc, 0x8000, v198
	s_nop 1
	v_addc_co_u32_e32 v131, vcc, 0, v199, vcc
	global_load_dwordx4 v[146:149], v[130:131], off offset:256
.LBB0_589:
	v_add_co_u32_e32 v130, vcc, 0x10000, v200
	s_nop 1
	v_addc_co_u32_e32 v131, vcc, 0, v201, vcc
	global_load_dwordx4 v[174:177], v[130:131], off nt
	s_and_b64 vcc, exec, s[4:5]
	s_cbranch_vccnz .LBB0_591
	v_add_co_u32_e32 v130, vcc, 0x10000, v198
	s_nop 1
	v_addc_co_u32_e32 v131, vcc, 0, v199, vcc
	global_load_dwordx4 v[142:145], v[130:131], off
.LBB0_591:
	v_add_co_u32_e32 v130, vcc, 0x10000, v200
	s_nop 1
	v_addc_co_u32_e32 v131, vcc, 0, v201, vcc
	global_load_dwordx4 v[170:173], v[130:131], off offset:256 nt
	s_and_b64 vcc, exec, s[4:5]
	s_cbranch_vccnz .LBB0_593
	v_add_co_u32_e32 v130, vcc, 0x10000, v198
	s_nop 1
	v_addc_co_u32_e32 v131, vcc, 0, v199, vcc
	global_load_dwordx4 v[138:141], v[130:131], off offset:256
.LBB0_593:
	v_add_co_u32_e32 v130, vcc, 0x18000, v200
	s_nop 1
	v_addc_co_u32_e32 v131, vcc, 0, v201, vcc
	global_load_dwordx4 v[166:169], v[130:131], off nt
	s_and_b64 vcc, exec, s[4:5]
	s_cbranch_vccnz .LBB0_595
	v_add_co_u32_e32 v130, vcc, 0x18000, v198
	s_nop 1
	v_addc_co_u32_e32 v131, vcc, 0, v199, vcc
	global_load_dwordx4 v[134:137], v[130:131], off
.LBB0_595:
	v_add_co_u32_e32 v130, vcc, 0x18000, v200
	s_nop 1
	v_addc_co_u32_e32 v131, vcc, 0, v201, vcc
	global_load_dwordx4 v[162:165], v[130:131], off offset:256 nt
	s_and_b64 vcc, exec, s[4:5]
	s_cbranch_vccnz .LBB0_597
	v_add_co_u32_e32 v130, vcc, 0x18000, v198
	s_nop 1
	v_addc_co_u32_e32 v131, vcc, 0, v199, vcc
	global_load_dwordx4 v[130:133], v[130:131], off offset:256

;     __device__ __forceinline__ void operator()(acc_t& acc, const Unit& u, int wr, int wc, int fr, int fq) const {
;     ...
;         for (int ai = 0; ai < 2; ++ai) {
;             u32x4 ga[4][2], gb[4][2];
; #pragma unroll
;             for (int m = 0; m < 4; ++m)
; #pragma unroll
;                 for (int bj = 0; bj < 2; ++bj) { const size_t o = (size_t)(ai * HALF + m * 16) * D + HALF * bj; ga[m][bj] = *(const u32x4*)(Ga + o); if (br < 2) gb[m][bj] = *(const u32x4*)(Gb + o); }
.LBB0_653:
	v_add_co_u32_e32 v162, vcc, 0x40000, v200
	s_nop 1
	v_addc_co_u32_e32 v163, vcc, 0, v201, vcc
	global_load_dwordx4 v[190:193], v[162:163], off nt
	s_and_b64 vcc, exec, s[4:5]
	s_cbranch_vccnz .LBB0_655
	v_add_co_u32_e32 v158, vcc, 0x40000, v198
	s_nop 1
	v_addc_co_u32_e32 v159, vcc, 0, v199, vcc
	global_load_dwordx4 v[158:161], v[158:159], off
.LBB0_655:
	v_add_co_u32_e32 v162, vcc, 0x40000, v200
	s_nop 1
	v_addc_co_u32_e32 v163, vcc, 0, v201, vcc
	global_load_dwordx4 v[186:189], v[162:163], off offset:256 nt
	s_and_b64 vcc, exec, s[4:5]
	s_cbranch_vccnz .LBB0_657
	v_add_co_u32_e32 v154, vcc, 0x40000, v198
	s_nop 1
	v_addc_co_u32_e32 v155, vcc, 0, v199, vcc
	global_load_dwordx4 v[154:157], v[154:155], off offset:256
.LBB0_657:
	v_add_co_u32_e32 v162, vcc, 0x48000, v200
	s_nop 1
	v_addc_co_u32_e32 v163, vcc, 0, v201, vcc
	global_load_dwordx4 v[182:185], v[162:163], off nt
	s_and_b64 vcc, exec, s[4:5]
	s_cbranch_vccnz .LBB0_659
	v_add_co_u32_e32 v150, vcc, 0x48000, v198
	s_nop 1
	v_addc_co_u32_e32 v151, vcc, 0, v199, vcc
	global_load_dwordx4 v[150:153], v[150:151], off
.LBB0_659:
	v_add_co_u32_e32 v162, vcc, 0x48000, v200
	s_nop 1
	v_addc_co_u32_e32 v163, vcc, 0, v201, vcc
	global_load_dwordx4 v[178:181], v[162:163], off offset:256 nt
	s_and_b64 vcc, exec, s[4:5]
	s_cbranch_vccnz .LBB0_661
	v_add_co_u32_e32 v146, vcc, 0x48000, v198
	s_nop 1
	v_addc_co_u32_e32 v147, vcc, 0, v199, vcc
	global_load_dwordx4 v[146:149], v[146:147], off offset:256
.LBB0_661:
	v_add_co_u32_e32 v162, vcc, 0x50000, v200
	s_nop 1
	v_addc_co_u32_e32 v163, vcc, 0, v201, vcc
	global_load_dwordx4 v[174:177], v[162:163], off nt
	s_and_b64 vcc, exec, s[4:5]
	s_cbranch_vccnz .LBB0_663
	v_add_co_u32_e32 v142, vcc, 0x50000, v198
	s_nop 1
	v_addc_co_u32_e32 v143, vcc, 0, v199, vcc
	global_load_dwordx4 v[142:145], v[142:143], off
.LBB0_663:
	v_add_co_u32_e32 v162, vcc, 0x50000, v200
	s_nop 1
	v_addc_co_u32_e32 v163, vcc, 0, v201, vcc
	global_load_dwordx4 v[170:173], v[162:163], off offset:256 nt
	s_and_b64 vcc, exec, s[4:5]
	s_cbranch_vccnz .LBB0_665
	v_add_co_u32_e32 v138, vcc, 0x50000, v198
	s_nop 1
	v_addc_co_u32_e32 v139, vcc, 0, v199, vcc
	global_load_dwordx4 v[138:141], v[138:139], off offset:256
.LBB0_665:
	v_add_co_u32_e32 v162, vcc, 0x58000, v200
	s_nop 1
	v_addc_co_u32_e32 v163, vcc, 0, v201, vcc
	global_load_dwordx4 v[166:169], v[162:163], off nt
	s_and_b64 vcc, exec, s[4:5]
	s_cbranch_vccnz .LBB0_667
	v_add_co_u32_e32 v134, vcc, 0x58000, v198
	s_nop 1
	v_addc_co_u32_e32 v135, vcc, 0, v199, vcc
	global_load_dwordx4 v[134:137], v[134:135], off
.LBB0_667:
	v_add_co_u32_e32 v162, vcc, 0x58000, v200
	s_nop 1
	v_addc_co_u32_e32 v163, vcc, 0, v201, vcc
	global_load_dwordx4 v[162:165], v[162:163], off offset:256 nt
	s_and_b64 vcc, exec, s[4:5]
	s_cbranch_vccnz .LBB0_669
	v_add_co_u32_e32 v130, vcc, 0x58000, v198
	s_nop 1
	v_addc_co_u32_e32 v131, vcc, 0, v199, vcc
	global_load_dwordx4 v[130:133], v[130:131], off offset:256

; __device__ __forceinline__ float bflo(unsigned w) { return __uint_as_float(w << 16); }
; __device__ __forceinline__ float bfhi(unsigned w) { return __uint_as_float(w & 0xffff0000u); }
; #define PG8_LAS __attribute__((address_space(3)))
; __device__ __forceinline__ unsigned cvt_pk_bf16(float lo, float hi) { f32x2c v = {lo, hi}; bf16x2c b = __builtin_convertvector(v, bf16x2c); return __builtin_bit_cast(unsigned, b); }
; __device__ __forceinline__ float bflo(unsigned w) { return __uint_as_float(w << 16); }
; __device__ __forceinline__ float bfhi(unsigned w) { return __uint_as_float(w & 0xffff0000u); }
; __device__ __forceinline__ float xsum16(float v) { auto r = __builtin_amdgcn_permlane16_swap(__float_as_uint(v), __float_as_uint(v), false, false); return __uint_as_float(r[0]) + __uint_as_float(r[1]); }
; __device__ __forceinline__ float xsum32(float v) { auto r = __builtin_amdgcn_permlane32_swap(__float_as_uint(v), __float_as_uint(v), false, false); return __uint_as_float(r[0]) + __uint_as_float(r[1]); }
;     __device__ __forceinline__ void fused(const acc_t& acc, const Unit& u, int wr, int wc, int fr, int fq, PG8_LAS unsigned char* lds, int, int) const {
;         PG8_LAS float* red = (PG8_LAS float*)lds;
;         const int row0 = u.pm * BM + wr * 64 + fr, col0 = u.pn * BM + wc * 32 + 8 * fq;
; #pragma unroll
;         for (int ai = 0; ai < 2; ++ai)
; #pragma unroll
;             for (int m = 0; m < 4; ++m) { const int row = row0 + ai * HALF + m * 16; const size_t off = (size_t)row * D + col0; float ss = 0.f;
; #pragma unroll
;                 for (int bj = 0; bj < 2; ++bj) { const size_t o = off + bj * HALF;
;                     const f32x4 r0 = *(const f32x4*)(x + o) + acc[ai][bj][m][0], r1 = *(const f32x4*)(x + o + 4) + acc[ai][bj][m][1];
;                     u32x4 w; w.x = cvt_pk_bf16(r0[0], r0[1]); w.y = cvt_pk_bf16(r0[2], r0[3]); w.z = cvt_pk_bf16(r1[0], r1[1]); w.w = cvt_pk_bf16(r1[2], r1[3]); *(u32x4*)(A2 + o) = w;
;                     const float q0 = bflo(w.x), q1 = bfhi(w.x), q2 = bflo(w.y), q3 = bfhi(w.y), q4 = bflo(w.z), q5 = bfhi(w.z), q6 = bflo(w.w), q7 = bfhi(w.w);
;                     ss += ((q0 * q0 + q1 * q1) + (q2 * q2 + q3 * q3)) + ((q4 * q4 + q5 * q5) + (q6 * q6 + q7 * q7)); }
;                 ss = xsum16(ss); ss = xsum32(ss);
;                 if (fq == 0) red[(ai * HALF + wr * 64 + m * 16 + fr) * 4 + wc] = ss;
.LBB0_804:
	s_lshl_b32 s2, s11, 5
	s_lshl_b32 s1, s10, 8
	s_lshl_b32 s3, s0, 8
	s_or_b32 s2, s3, s2
	v_add_u32_e32 v132, s1, v134
	v_lshl_or_b32 v130, v139, 3, s2
	v_ashrrev_i32_e32 v133, 31, v132
	v_ashrrev_i32_e32 v131, 31, v130
	v_lshlrev_b64 v[136:137], 10, v[132:133]
	v_readlane_b32 s12, v247, 2
	v_lshl_add_u64 v[136:137], v[136:137], 0, v[130:131]
	v_readlane_b32 s13, v247, 3
	s_barrier
	v_readlane_b32 s4, v247, 49
	v_lshl_add_u64 v[148:149], v[136:137], 2, s[12:13]
	global_load_dwordx4 v[140:143], v[148:149], off nt
	global_load_dwordx4 v[144:147], v[148:149], off offset:16 nt
	v_lshlrev_b64 v[136:137], 1, v[136:137]
	v_readlane_b32 s5, v247, 50
	v_cmp_eq_u32_e32 vcc, 0, v139
	s_lshl_b32 s2, s11, 2
	v_lshl_add_u64 v[150:151], s[4:5], 0, v[136:137]
	v_or_b32_e32 v136, 0x100, v136
	v_lshl_add_u64 v[136:137], s[4:5], 0, v[136:137]
	s_add_i32 s2, s2, 0
	v_readlane_b32 s18, v247, 8
	v_readlane_b32 s19, v247, 9
	v_readlane_b32 s14, v247, 4
	v_readlane_b32 s15, v247, 5
	v_readlane_b32 s16, v247, 6
	v_readlane_b32 s17, v247, 7
	v_readlane_b32 s20, v247, 10
	v_readlane_b32 s21, v247, 11
	v_readlane_b32 s22, v247, 12
	v_readlane_b32 s23, v247, 13
	v_readlane_b32 s24, v247, 14
	v_readlane_b32 s25, v247, 15
	v_readlane_b32 s26, v247, 16
	v_readlane_b32 s27, v247, 17
	s_waitcnt vmcnt(0)
	v_pk_add_f32 v[128:129], v[128:129], v[142:143]
	v_pk_add_f32 v[126:127], v[126:127], v[140:141]
	v_pk_add_f32 v[140:141], v[124:125], v[146:147]
	v_pk_add_f32 v[124:125], v[122:123], v[144:145]
	v_cvt_pk_bf16_f32 v122, v126, v127
	v_cvt_pk_bf16_f32 v123, v128, v129
	v_cvt_pk_bf16_f32 v124, v124, v125
	v_cvt_pk_bf16_f32 v125, v140, v141
	global_store_dwordx4 v[150:151], v[122:125], off
	global_load_dwordx4 v[126:129], v[148:149], off offset:512 nt
	global_load_dwordx4 v[140:143], v[148:149], off offset:528 nt
	v_lshlrev_b32_e32 v135, 16, v122
	v_and_b32_e32 v122, 0xffff0000, v122
	v_lshlrev_b32_e32 v138, 16, v123
	v_and_b32_e32 v123, 0xffff0000, v123
	v_lshlrev_b32_e32 v139, 16, v124
	v_and_b32_e32 v124, 0xffff0000, v124
	v_lshlrev_b32_e32 v144, 16, v125
	v_and_b32_e32 v125, 0xffff0000, v125
	v_mul_f32_e32 v122, v122, v122
	v_mul_f32_e32 v123, v123, v123
	v_mul_f32_e32 v124, v124, v124
	v_mul_f32_e32 v125, v125, v125
	v_fmac_f32_e32 v122, v135, v135
	v_fmac_f32_e32 v123, v138, v138
	v_fmac_f32_e32 v124, v139, v139
	v_fmac_f32_e32 v125, v144, v144
	v_add_f32_e32 v122, v122, v123
	v_add_f32_e32 v123, v124, v125
	v_add_f32_e32 v124, v122, v123
	s_waitcnt vmcnt(1)
	v_pk_add_f32 v[120:121], v[120:121], v[128:129]
	v_pk_add_f32 v[118:119], v[118:119], v[126:127]
	s_waitcnt vmcnt(0)
	v_pk_add_f32 v[122:123], v[116:117], v[142:143]
	v_pk_add_f32 v[116:117], v[114:115], v[140:141]
	v_cvt_pk_bf16_f32 v114, v118, v119
	v_cvt_pk_bf16_f32 v115, v120, v121
	v_cvt_pk_bf16_f32 v116, v116, v117
	v_cvt_pk_bf16_f32 v117, v122, v123
	global_store_dwordx4 v[136:137], v[114:117], off
	v_lshlrev_b32_e32 v118, 16, v114
	v_lshlrev_b32_e32 v119, 16, v115
	v_and_b32_e32 v114, 0xffff0000, v114
	v_and_b32_e32 v115, 0xffff0000, v115
	v_lshlrev_b32_e32 v120, 16, v116
	v_and_b32_e32 v116, 0xffff0000, v116
	v_lshlrev_b32_e32 v121, 16, v117
	v_and_b32_e32 v117, 0xffff0000, v117
	v_mul_f32_e32 v114, v114, v114
	v_mul_f32_e32 v115, v115, v115
	v_mul_f32_e32 v116, v116, v116
	v_mul_f32_e32 v117, v117, v117
	v_fmac_f32_e32 v114, v118, v118
	v_fmac_f32_e32 v115, v119, v119
	v_fmac_f32_e32 v116, v120, v120
	v_fmac_f32_e32 v117, v121, v121
	v_add_f32_e32 v114, v114, v115
	v_add_f32_e32 v115, v116, v117
	v_add_f32_e32 v114, v114, v115
	v_add_f32_e32 v114, v124, v114
	v_mov_b32_e32 v115, v114
	s_nop 1
	v_permlane16_swap_b32_e32 v114, v115
	v_add_f32_e32 v115, v114, v115
	v_mov_b32_e32 v116, v115
	s_nop 1
	v_permlane32_swap_b32_e32 v115, v116
	v_lshl_add_u32 v114, v134, 4, s2
	s_and_saveexec_b64 s[2:3], vcc
	v_readlane_b32 s18, v247, 47
	v_readlane_b32 s19, v247, 48
	v_add_f32_e32 v115, v115, v116
	ds_write_b32 v114, v115
	s_or_b64 exec, exec, s[2:3]
	v_or_b32_e32 v116, 16, v132
	v_ashrrev_i32_e32 v117, 31, v116
	v_lshlrev_b64 v[116:117], 10, v[116:117]
	v_readlane_b32 s36, v247, 2
	v_lshl_add_u64 v[124:125], v[116:117], 0, v[130:131]
	v_readlane_b32 s37, v247, 3
	v_readlane_b32 s2, v247, 49
	v_readlane_b32 s3, v247, 50
	v_lshl_add_u64 v[126:127], v[124:125], 2, s[36:37]
	global_load_dwordx4 v[116:119], v[126:127], off nt
	global_load_dwordx4 v[120:123], v[126:127], off offset:16 nt
	v_lshlrev_b64 v[124:125], 1, v[124:125]
	v_lshl_add_u64 v[128:129], s[2:3], 0, v[124:125]
	v_or_b32_e32 v124, 0x100, v124
	v_readlane_b32 s38, v247, 4
	v_readlane_b32 s39, v247, 5
	v_readlane_b32 s40, v247, 6
	v_readlane_b32 s41, v247, 7
	v_readlane_b32 s42, v247, 8
	v_readlane_b32 s43, v247, 9
	v_readlane_b32 s44, v247, 10
	v_readlane_b32 s45, v247, 11
	v_readlane_b32 s46, v247, 12
	v_readlane_b32 s47, v247, 13
	v_readlane_b32 s48, v247, 14
	v_readlane_b32 s49, v247, 15
	v_readlane_b32 s50, v247, 16
	v_readlane_b32 s51, v247, 17
	s_waitcnt vmcnt(1)
	v_pk_add_f32 v[112:113], v[112:113], v[118:119]
	v_pk_add_f32 v[110:111], v[110:111], v[116:117]
	s_waitcnt vmcnt(0)
; __device__ __forceinline__ float bflo(unsigned w) { return __uint_as_float(w << 16); }
; __device__ __forceinline__ float bfhi(unsigned w) { return __uint_as_float(w & 0xffff0000u); }
; __device__ __forceinline__ unsigned cvt_pk_bf16(float lo, float hi) { f32x2c v = {lo, hi}; bf16x2c b = __builtin_convertvector(v, bf16x2c); return __builtin_bit_cast(unsigned, b); }
; __device__ __forceinline__ float bflo(unsigned w) { return __uint_as_float(w << 16); }
; __device__ __forceinline__ float bfhi(unsigned w) { return __uint_as_float(w & 0xffff0000u); }
; __device__ __forceinline__ float xsum16(float v) { auto r = __builtin_amdgcn_permlane16_swap(__float_as_uint(v), __float_as_uint(v), false, false); return __uint_as_float(r[0]) + __uint_as_float(r[1]); }
; __device__ __forceinline__ float xsum32(float v) { auto r = __builtin_amdgcn_permlane32_swap(__float_as_uint(v), __float_as_uint(v), false, false); return __uint_as_float(r[0]) + __uint_as_float(r[1]); }
;     __device__ __forceinline__ void fused(const acc_t& acc, const Unit& u, int wr, int wc, int fr, int fq, PG8_LAS unsigned char* lds, int, int) const {
;     ...
;             for (int m = 0; m < 4; ++m) { const int row = row0 + ai * HALF + m * 16; const size_t off = (size_t)row * D + col0; float ss = 0.f;
; #pragma unroll
;                 for (int bj = 0; bj < 2; ++bj) { const size_t o = off + bj * HALF;
;                     const f32x4 r0 = *(const f32x4*)(x + o) + acc[ai][bj][m][0], r1 = *(const f32x4*)(x + o + 4) + acc[ai][bj][m][1];
;                     u32x4 w; w.x = cvt_pk_bf16(r0[0], r0[1]); w.y = cvt_pk_bf16(r0[2], r0[3]); w.z = cvt_pk_bf16(r1[0], r1[1]); w.w = cvt_pk_bf16(r1[2], r1[3]); *(u32x4*)(A2 + o) = w;
;                     const float q0 = bflo(w.x), q1 = bfhi(w.x), q2 = bflo(w.y), q3 = bfhi(w.y), q4 = bflo(w.z), q5 = bfhi(w.z), q6 = bflo(w.w), q7 = bfhi(w.w);
;                     ss += ((q0 * q0 + q1 * q1) + (q2 * q2 + q3 * q3)) + ((q4 * q4 + q5 * q5) + (q6 * q6 + q7 * q7)); }
;                 ss = xsum16(ss); ss = xsum32(ss);
;                 if (fq == 0) red[(ai * HALF + wr * 64 + m * 16 + fr) * 4 + wc] = ss;
	v_pk_add_f32 v[116:117], v[108:109], v[122:123]
	v_pk_add_f32 v[108:109], v[106:107], v[120:121]
	v_cvt_pk_bf16_f32 v106, v110, v111
	v_cvt_pk_bf16_f32 v107, v112, v113
	v_cvt_pk_bf16_f32 v108, v108, v109
	v_cvt_pk_bf16_f32 v109, v116, v117
	global_store_dwordx4 v[128:129], v[106:109], off
	global_load_dwordx4 v[110:113], v[126:127], off offset:512 nt
	global_load_dwordx4 v[116:119], v[126:127], off offset:528 nt
	v_lshl_add_u64 v[120:121], s[2:3], 0, v[124:125]
	v_lshlrev_b32_e32 v115, 16, v106
	v_and_b32_e32 v106, 0xffff0000, v106
	v_lshlrev_b32_e32 v122, 16, v107
	v_and_b32_e32 v107, 0xffff0000, v107
	v_lshlrev_b32_e32 v123, 16, v108
	v_and_b32_e32 v108, 0xffff0000, v108
	v_lshlrev_b32_e32 v124, 16, v109
	v_and_b32_e32 v109, 0xffff0000, v109
	v_mul_f32_e32 v106, v106, v106
	v_mul_f32_e32 v107, v107, v107
	v_mul_f32_e32 v108, v108, v108
	v_mul_f32_e32 v109, v109, v109
	v_fmac_f32_e32 v106, v115, v115
	v_fmac_f32_e32 v107, v122, v122
	v_fmac_f32_e32 v108, v123, v123
	v_fmac_f32_e32 v109, v124, v124
	v_add_f32_e32 v106, v106, v107
	v_add_f32_e32 v107, v108, v109
	v_add_f32_e32 v108, v106, v107
	s_waitcnt vmcnt(1)
	v_pk_add_f32 v[104:105], v[104:105], v[112:113]
	v_pk_add_f32 v[102:103], v[102:103], v[110:111]
	s_waitcnt vmcnt(0)
	v_pk_add_f32 v[106:107], v[100:101], v[118:119]
	v_pk_add_f32 v[100:101], v[98:99], v[116:117]
	v_cvt_pk_bf16_f32 v98, v102, v103
	v_cvt_pk_bf16_f32 v99, v104, v105
	v_cvt_pk_bf16_f32 v100, v100, v101
	v_cvt_pk_bf16_f32 v101, v106, v107
	global_store_dwordx4 v[120:121], v[98:101], off
	v_lshlrev_b32_e32 v102, 16, v98
	v_lshlrev_b32_e32 v103, 16, v99
	v_and_b32_e32 v98, 0xffff0000, v98
	v_and_b32_e32 v99, 0xffff0000, v99
	v_lshlrev_b32_e32 v104, 16, v100
	v_and_b32_e32 v100, 0xffff0000, v100
	v_lshlrev_b32_e32 v105, 16, v101
	v_and_b32_e32 v101, 0xffff0000, v101
	v_mul_f32_e32 v98, v98, v98
	v_mul_f32_e32 v99, v99, v99
	v_mul_f32_e32 v100, v100, v100
	v_mul_f32_e32 v101, v101, v101
	v_fmac_f32_e32 v98, v102, v102
	v_fmac_f32_e32 v99, v103, v103
	v_fmac_f32_e32 v100, v104, v104
	v_fmac_f32_e32 v101, v105, v105
	v_add_f32_e32 v98, v98, v99
	v_add_f32_e32 v99, v100, v101
	v_add_f32_e32 v98, v98, v99
	v_add_f32_e32 v98, v108, v98
	v_mov_b32_e32 v99, v98
	s_nop 1
	v_permlane16_swap_b32_e32 v98, v99
	v_add_f32_e32 v98, v98, v99
	v_mov_b32_e32 v99, v98
	s_nop 1
	v_permlane32_swap_b32_e32 v98, v99
	s_and_saveexec_b64 s[2:3], vcc
	v_add_f32_e32 v98, v98, v99
	ds_write_b32 v114, v98 offset:256
	s_or_b64 exec, exec, s[2:3]
	v_or_b32_e32 v98, 32, v132
	v_ashrrev_i32_e32 v99, 31, v98
	v_lshlrev_b64 v[98:99], 10, v[98:99]
	v_readlane_b32 s36, v247, 2
	v_lshl_add_u64 v[106:107], v[98:99], 0, v[130:131]
	v_readlane_b32 s37, v247, 3
	v_readlane_b32 s2, v247, 49
	v_readlane_b32 s3, v247, 50
	v_lshl_add_u64 v[108:109], v[106:107], 2, s[36:37]
	global_load_dwordx4 v[98:101], v[108:109], off nt
	global_load_dwordx4 v[102:105], v[108:109], off offset:16 nt
	v_lshlrev_b64 v[106:107], 1, v[106:107]
	v_lshl_add_u64 v[110:111], s[2:3], 0, v[106:107]
	v_or_b32_e32 v106, 0x100, v106
	v_readlane_b32 s38, v247, 4
	v_readlane_b32 s39, v247, 5
	v_readlane_b32 s40, v247, 6
	v_readlane_b32 s41, v247, 7
	v_readlane_b32 s42, v247, 8
	v_readlane_b32 s43, v247, 9
	v_readlane_b32 s44, v247, 10
	v_readlane_b32 s45, v247, 11
	v_readlane_b32 s46, v247, 12
	v_readlane_b32 s47, v247, 13
	v_readlane_b32 s48, v247, 14
	v_readlane_b32 s49, v247, 15
	v_readlane_b32 s50, v247, 16
	v_readlane_b32 s51, v247, 17
	s_waitcnt vmcnt(1)
	v_pk_add_f32 v[96:97], v[96:97], v[100:101]
	v_pk_add_f32 v[94:95], v[94:95], v[98:99]
	s_waitcnt vmcnt(0)
	v_pk_add_f32 v[98:99], v[92:93], v[104:105]
	v_pk_add_f32 v[92:93], v[90:91], v[102:103]
	v_cvt_pk_bf16_f32 v90, v94, v95
	v_cvt_pk_bf16_f32 v91, v96, v97
	v_cvt_pk_bf16_f32 v92, v92, v93
	v_cvt_pk_bf16_f32 v93, v98, v99
	global_store_dwordx4 v[110:111], v[90:93], off
	global_load_dwordx4 v[94:97], v[108:109], off offset:512 nt
	global_load_dwordx4 v[98:101], v[108:109], off offset:528 nt
	v_lshl_add_u64 v[102:103], s[2:3], 0, v[106:107]
	v_lshlrev_b32_e32 v104, 16, v90
	v_and_b32_e32 v90, 0xffff0000, v90
	v_lshlrev_b32_e32 v105, 16, v91
	v_and_b32_e32 v91, 0xffff0000, v91
	v_lshlrev_b32_e32 v106, 16, v92
	v_and_b32_e32 v92, 0xffff0000, v92
	v_lshlrev_b32_e32 v107, 16, v93
	v_and_b32_e32 v93, 0xffff0000, v93
	v_mul_f32_e32 v90, v90, v90
	v_mul_f32_e32 v91, v91, v91
	v_mul_f32_e32 v92, v92, v92
	v_mul_f32_e32 v93, v93, v93
	v_fmac_f32_e32 v90, v104, v104
	v_fmac_f32_e32 v91, v105, v105
	v_fmac_f32_e32 v92, v106, v106
	v_fmac_f32_e32 v93, v107, v107
	v_add_f32_e32 v90, v90, v91
	v_add_f32_e32 v91, v92, v93
	v_add_f32_e32 v92, v90, v91
	s_waitcnt vmcnt(1)
	v_pk_add_f32 v[88:89], v[88:89], v[96:97]
	v_pk_add_f32 v[86:87], v[86:87], v[94:95]
	s_waitcnt vmcnt(0)
; __device__ __forceinline__ float bflo(unsigned w) { return __uint_as_float(w << 16); }
; __device__ __forceinline__ float bfhi(unsigned w) { return __uint_as_float(w & 0xffff0000u); }
; __device__ __forceinline__ unsigned cvt_pk_bf16(float lo, float hi) { f32x2c v = {lo, hi}; bf16x2c b = __builtin_convertvector(v, bf16x2c); return __builtin_bit_cast(unsigned, b); }
; __device__ __forceinline__ float bflo(unsigned w) { return __uint_as_float(w << 16); }
; __device__ __forceinline__ float bfhi(unsigned w) { return __uint_as_float(w & 0xffff0000u); }
; __device__ __forceinline__ float xsum16(float v) { auto r = __builtin_amdgcn_permlane16_swap(__float_as_uint(v), __float_as_uint(v), false, false); return __uint_as_float(r[0]) + __uint_as_float(r[1]); }
; __device__ __forceinline__ float xsum32(float v) { auto r = __builtin_amdgcn_permlane32_swap(__float_as_uint(v), __float_as_uint(v), false, false); return __uint_as_float(r[0]) + __uint_as_float(r[1]); }
;     __device__ __forceinline__ void fused(const acc_t& acc, const Unit& u, int wr, int wc, int fr, int fq, PG8_LAS unsigned char* lds, int, int) const {
;     ...
;             for (int m = 0; m < 4; ++m) { const int row = row0 + ai * HALF + m * 16; const size_t off = (size_t)row * D + col0; float ss = 0.f;
; #pragma unroll
;                 for (int bj = 0; bj < 2; ++bj) { const size_t o = off + bj * HALF;
;                     const f32x4 r0 = *(const f32x4*)(x + o) + acc[ai][bj][m][0], r1 = *(const f32x4*)(x + o + 4) + acc[ai][bj][m][1];
;                     u32x4 w; w.x = cvt_pk_bf16(r0[0], r0[1]); w.y = cvt_pk_bf16(r0[2], r0[3]); w.z = cvt_pk_bf16(r1[0], r1[1]); w.w = cvt_pk_bf16(r1[2], r1[3]); *(u32x4*)(A2 + o) = w;
;                     const float q0 = bflo(w.x), q1 = bfhi(w.x), q2 = bflo(w.y), q3 = bfhi(w.y), q4 = bflo(w.z), q5 = bfhi(w.z), q6 = bflo(w.w), q7 = bfhi(w.w);
;                     ss += ((q0 * q0 + q1 * q1) + (q2 * q2 + q3 * q3)) + ((q4 * q4 + q5 * q5) + (q6 * q6 + q7 * q7)); }
;                 ss = xsum16(ss); ss = xsum32(ss);
;                 if (fq == 0) red[(ai * HALF + wr * 64 + m * 16 + fr) * 4 + wc] = ss;
	v_pk_add_f32 v[90:91], v[84:85], v[100:101]
	v_pk_add_f32 v[84:85], v[82:83], v[98:99]
	v_cvt_pk_bf16_f32 v82, v86, v87
	v_cvt_pk_bf16_f32 v83, v88, v89
	v_cvt_pk_bf16_f32 v84, v84, v85
	v_cvt_pk_bf16_f32 v85, v90, v91
	global_store_dwordx4 v[102:103], v[82:85], off
	v_lshlrev_b32_e32 v86, 16, v82
	v_lshlrev_b32_e32 v87, 16, v83
	v_and_b32_e32 v82, 0xffff0000, v82
	v_and_b32_e32 v83, 0xffff0000, v83
	v_lshlrev_b32_e32 v88, 16, v84
	v_and_b32_e32 v84, 0xffff0000, v84
	v_lshlrev_b32_e32 v89, 16, v85
	v_and_b32_e32 v85, 0xffff0000, v85
	v_mul_f32_e32 v82, v82, v82
	v_mul_f32_e32 v83, v83, v83
	v_mul_f32_e32 v84, v84, v84
	v_mul_f32_e32 v85, v85, v85
	v_fmac_f32_e32 v82, v86, v86
	v_fmac_f32_e32 v83, v87, v87
	v_fmac_f32_e32 v84, v88, v88
	v_fmac_f32_e32 v85, v89, v89
	v_add_f32_e32 v82, v82, v83
	v_add_f32_e32 v83, v84, v85
	v_add_f32_e32 v82, v82, v83
	v_add_f32_e32 v82, v92, v82
	v_mov_b32_e32 v83, v82
	s_nop 1
	v_permlane16_swap_b32_e32 v82, v83
	v_add_f32_e32 v82, v82, v83
	v_mov_b32_e32 v83, v82
	s_nop 1
	v_permlane32_swap_b32_e32 v82, v83
	s_and_saveexec_b64 s[2:3], vcc
	v_add_f32_e32 v82, v82, v83
	ds_write_b32 v114, v82 offset:512
	s_or_b64 exec, exec, s[2:3]
	v_or_b32_e32 v82, 48, v132
	v_ashrrev_i32_e32 v83, 31, v82
	v_lshlrev_b64 v[82:83], 10, v[82:83]
	v_readlane_b32 s36, v247, 2
	v_lshl_add_u64 v[90:91], v[82:83], 0, v[130:131]
	v_readlane_b32 s37, v247, 3
	v_readlane_b32 s2, v247, 49
	v_readlane_b32 s3, v247, 50
	v_lshl_add_u64 v[92:93], v[90:91], 2, s[36:37]
	global_load_dwordx4 v[82:85], v[92:93], off nt
	global_load_dwordx4 v[86:89], v[92:93], off offset:16 nt
	v_lshlrev_b64 v[90:91], 1, v[90:91]
	v_lshl_add_u64 v[94:95], s[2:3], 0, v[90:91]
	v_or_b32_e32 v90, 0x100, v90
	v_readlane_b32 s38, v247, 4
	v_readlane_b32 s39, v247, 5
	v_readlane_b32 s40, v247, 6
	v_readlane_b32 s41, v247, 7
	v_readlane_b32 s42, v247, 8
	v_readlane_b32 s43, v247, 9
	v_readlane_b32 s44, v247, 10
	v_readlane_b32 s45, v247, 11
	v_readlane_b32 s46, v247, 12
	v_readlane_b32 s47, v247, 13
	v_readlane_b32 s48, v247, 14
	v_readlane_b32 s49, v247, 15
	v_readlane_b32 s50, v247, 16
	v_readlane_b32 s51, v247, 17
	s_waitcnt vmcnt(1)
	v_pk_add_f32 v[80:81], v[80:81], v[84:85]
	v_pk_add_f32 v[78:79], v[78:79], v[82:83]
	s_waitcnt vmcnt(0)
	v_pk_add_f32 v[82:83], v[76:77], v[88:89]
	v_pk_add_f32 v[76:77], v[74:75], v[86:87]
	v_cvt_pk_bf16_f32 v74, v78, v79
	v_cvt_pk_bf16_f32 v75, v80, v81
	v_cvt_pk_bf16_f32 v76, v76, v77
	v_cvt_pk_bf16_f32 v77, v82, v83
	global_store_dwordx4 v[94:95], v[74:77], off
	global_load_dwordx4 v[78:81], v[92:93], off offset:512 nt
	global_load_dwordx4 v[82:85], v[92:93], off offset:528 nt
	v_lshl_add_u64 v[86:87], s[2:3], 0, v[90:91]
	v_lshlrev_b32_e32 v88, 16, v74
	v_and_b32_e32 v74, 0xffff0000, v74
	v_lshlrev_b32_e32 v89, 16, v75
	v_and_b32_e32 v75, 0xffff0000, v75
	v_lshlrev_b32_e32 v90, 16, v76
	v_and_b32_e32 v76, 0xffff0000, v76
	v_lshlrev_b32_e32 v91, 16, v77
	v_and_b32_e32 v77, 0xffff0000, v77
	v_mul_f32_e32 v74, v74, v74
	v_mul_f32_e32 v75, v75, v75
	v_mul_f32_e32 v76, v76, v76
	v_mul_f32_e32 v77, v77, v77
	v_fmac_f32_e32 v74, v88, v88
	v_fmac_f32_e32 v75, v89, v89
	v_fmac_f32_e32 v76, v90, v90
	v_fmac_f32_e32 v77, v91, v91
	v_add_f32_e32 v74, v74, v75
	v_add_f32_e32 v75, v76, v77
	v_add_f32_e32 v76, v74, v75
	s_waitcnt vmcnt(1)
	v_pk_add_f32 v[72:73], v[72:73], v[80:81]
	v_pk_add_f32 v[70:71], v[70:71], v[78:79]
	s_waitcnt vmcnt(0)
	v_pk_add_f32 v[74:75], v[68:69], v[84:85]
	v_pk_add_f32 v[68:69], v[66:67], v[82:83]
	v_cvt_pk_bf16_f32 v66, v70, v71
	v_cvt_pk_bf16_f32 v67, v72, v73
	v_cvt_pk_bf16_f32 v68, v68, v69
	v_cvt_pk_bf16_f32 v69, v74, v75
	global_store_dwordx4 v[86:87], v[66:69], off
	v_lshlrev_b32_e32 v70, 16, v66
	v_lshlrev_b32_e32 v71, 16, v67
	v_and_b32_e32 v66, 0xffff0000, v66
	v_and_b32_e32 v67, 0xffff0000, v67
	v_lshlrev_b32_e32 v72, 16, v68
	v_and_b32_e32 v68, 0xffff0000, v68
	v_lshlrev_b32_e32 v73, 16, v69
	v_and_b32_e32 v69, 0xffff0000, v69
	v_mul_f32_e32 v66, v66, v66
	v_mul_f32_e32 v67, v67, v67
	v_mul_f32_e32 v68, v68, v68
	v_mul_f32_e32 v69, v69, v69
	v_fmac_f32_e32 v66, v70, v70
	v_fmac_f32_e32 v67, v71, v71
	v_fmac_f32_e32 v68, v72, v72
	v_fmac_f32_e32 v69, v73, v73
	v_add_f32_e32 v66, v66, v67
	v_add_f32_e32 v67, v68, v69
	v_add_f32_e32 v66, v66, v67
	v_add_f32_e32 v66, v76, v66
	v_mov_b32_e32 v67, v66
	s_nop 1
	v_permlane16_swap_b32_e32 v66, v67
	v_add_f32_e32 v66, v66, v67
	v_mov_b32_e32 v67, v66
	s_nop 1
	v_permlane32_swap_b32_e32 v66, v67
	s_and_saveexec_b64 s[2:3], vcc
	v_add_f32_e32 v66, v66, v67
	ds_write_b32 v114, v66 offset:768
	s_or_b64 exec, exec, s[2:3]
	v_lshlrev_b64 v[66:67], 10, v[132:133]
	v_lshl_add_u64 v[66:67], v[66:67], 0, v[130:131]
	s_mov_b64 s[2:3], 0x20000
	v_readlane_b32 s36, v247, 2
	v_lshl_add_u64 v[76:77], v[66:67], 0, s[2:3]
	v_readlane_b32 s37, v247, 3
	v_readlane_b32 s2, v247, 49
	v_readlane_b32 s3, v247, 50
	v_lshl_add_u64 v[78:79], v[76:77], 2, s[36:37]
	global_load_dwordx4 v[68:71], v[78:79], off nt
	global_load_dwordx4 v[72:75], v[78:79], off offset:16 nt
	v_lshlrev_b64 v[76:77], 1, v[76:77]
	v_lshl_add_u64 v[80:81], s[2:3], 0, v[76:77]
	v_or_b32_e32 v76, 0x100, v76
	v_readlane_b32 s38, v247, 4
	v_readlane_b32 s39, v247, 5
	v_readlane_b32 s40, v247, 6
	v_readlane_b32 s41, v247, 7
	v_readlane_b32 s42, v247, 8
	v_readlane_b32 s43, v247, 9
	v_readlane_b32 s44, v247, 10
	v_readlane_b32 s45, v247, 11
	v_readlane_b32 s46, v247, 12
	v_readlane_b32 s47, v247, 13
	v_readlane_b32 s48, v247, 14
	v_readlane_b32 s49, v247, 15
	v_readlane_b32 s50, v247, 16
	v_readlane_b32 s51, v247, 17
	s_waitcnt vmcnt(1)
	v_pk_add_f32 v[64:65], v[64:65], v[70:71]
	v_pk_add_f32 v[62:63], v[62:63], v[68:69]
	s_waitcnt vmcnt(0)
; __device__ __forceinline__ float bflo(unsigned w) { return __uint_as_float(w << 16); }
; __device__ __forceinline__ float bfhi(unsigned w) { return __uint_as_float(w & 0xffff0000u); }
; __device__ __forceinline__ unsigned cvt_pk_bf16(float lo, float hi) { f32x2c v = {lo, hi}; bf16x2c b = __builtin_convertvector(v, bf16x2c); return __builtin_bit_cast(unsigned, b); }
; __device__ __forceinline__ float bflo(unsigned w) { return __uint_as_float(w << 16); }
; __device__ __forceinline__ float bfhi(unsigned w) { return __uint_as_float(w & 0xffff0000u); }
; __device__ __forceinline__ float xsum16(float v) { auto r = __builtin_amdgcn_permlane16_swap(__float_as_uint(v), __float_as_uint(v), false, false); return __uint_as_float(r[0]) + __uint_as_float(r[1]); }
; __device__ __forceinline__ float xsum32(float v) { auto r = __builtin_amdgcn_permlane32_swap(__float_as_uint(v), __float_as_uint(v), false, false); return __uint_as_float(r[0]) + __uint_as_float(r[1]); }
;     __device__ __forceinline__ void fused(const acc_t& acc, const Unit& u, int wr, int wc, int fr, int fq, PG8_LAS unsigned char* lds, int, int) const {
;     ...
;             for (int m = 0; m < 4; ++m) { const int row = row0 + ai * HALF + m * 16; const size_t off = (size_t)row * D + col0; float ss = 0.f;
; #pragma unroll
;                 for (int bj = 0; bj < 2; ++bj) { const size_t o = off + bj * HALF;
;                     const f32x4 r0 = *(const f32x4*)(x + o) + acc[ai][bj][m][0], r1 = *(const f32x4*)(x + o + 4) + acc[ai][bj][m][1];
;                     u32x4 w; w.x = cvt_pk_bf16(r0[0], r0[1]); w.y = cvt_pk_bf16(r0[2], r0[3]); w.z = cvt_pk_bf16(r1[0], r1[1]); w.w = cvt_pk_bf16(r1[2], r1[3]); *(u32x4*)(A2 + o) = w;
;                     const float q0 = bflo(w.x), q1 = bfhi(w.x), q2 = bflo(w.y), q3 = bfhi(w.y), q4 = bflo(w.z), q5 = bfhi(w.z), q6 = bflo(w.w), q7 = bfhi(w.w);
;                     ss += ((q0 * q0 + q1 * q1) + (q2 * q2 + q3 * q3)) + ((q4 * q4 + q5 * q5) + (q6 * q6 + q7 * q7)); }
;                 ss = xsum16(ss); ss = xsum32(ss);
;                 if (fq == 0) red[(ai * HALF + wr * 64 + m * 16 + fr) * 4 + wc] = ss;
	v_pk_add_f32 v[68:69], v[60:61], v[74:75]
	v_pk_add_f32 v[60:61], v[58:59], v[72:73]
	v_cvt_pk_bf16_f32 v58, v62, v63
	v_cvt_pk_bf16_f32 v59, v64, v65
	v_cvt_pk_bf16_f32 v60, v60, v61
	v_cvt_pk_bf16_f32 v61, v68, v69
	global_store_dwordx4 v[80:81], v[58:61], off
	global_load_dwordx4 v[62:65], v[78:79], off offset:512 nt
	global_load_dwordx4 v[68:71], v[78:79], off offset:528 nt
	v_lshl_add_u64 v[72:73], s[2:3], 0, v[76:77]
	v_lshlrev_b32_e32 v74, 16, v58
	v_and_b32_e32 v58, 0xffff0000, v58
	v_lshlrev_b32_e32 v75, 16, v59
	v_and_b32_e32 v59, 0xffff0000, v59
	v_lshlrev_b32_e32 v76, 16, v60
	v_and_b32_e32 v60, 0xffff0000, v60
	v_lshlrev_b32_e32 v77, 16, v61
	v_and_b32_e32 v61, 0xffff0000, v61
	v_mul_f32_e32 v58, v58, v58
	v_mul_f32_e32 v59, v59, v59
	v_mul_f32_e32 v60, v60, v60
	v_mul_f32_e32 v61, v61, v61
	v_fmac_f32_e32 v58, v74, v74
	v_fmac_f32_e32 v59, v75, v75
	v_fmac_f32_e32 v60, v76, v76
	v_fmac_f32_e32 v61, v77, v77
	v_add_f32_e32 v58, v58, v59
	v_add_f32_e32 v59, v60, v61
	v_add_f32_e32 v60, v58, v59
	s_waitcnt vmcnt(1)
	v_pk_add_f32 v[56:57], v[56:57], v[64:65]
	v_pk_add_f32 v[54:55], v[54:55], v[62:63]
	s_waitcnt vmcnt(0)
	v_pk_add_f32 v[58:59], v[52:53], v[70:71]
	v_pk_add_f32 v[52:53], v[50:51], v[68:69]
	v_cvt_pk_bf16_f32 v50, v54, v55
	v_cvt_pk_bf16_f32 v51, v56, v57
	v_cvt_pk_bf16_f32 v52, v52, v53
	v_cvt_pk_bf16_f32 v53, v58, v59
	global_store_dwordx4 v[72:73], v[50:53], off
	v_lshlrev_b32_e32 v54, 16, v50
	v_lshlrev_b32_e32 v55, 16, v51
	v_and_b32_e32 v50, 0xffff0000, v50
	v_and_b32_e32 v51, 0xffff0000, v51
	v_lshlrev_b32_e32 v56, 16, v52
	v_and_b32_e32 v52, 0xffff0000, v52
	v_lshlrev_b32_e32 v57, 16, v53
	v_and_b32_e32 v53, 0xffff0000, v53
	v_mul_f32_e32 v50, v50, v50
	v_mul_f32_e32 v51, v51, v51
	v_mul_f32_e32 v52, v52, v52
	v_mul_f32_e32 v53, v53, v53
	v_fmac_f32_e32 v50, v54, v54
	v_fmac_f32_e32 v51, v55, v55
	v_fmac_f32_e32 v52, v56, v56
	v_fmac_f32_e32 v53, v57, v57
	v_add_f32_e32 v50, v50, v51
	v_add_f32_e32 v51, v52, v53
	v_add_f32_e32 v50, v50, v51
	v_add_f32_e32 v50, v60, v50
	v_mov_b32_e32 v51, v50
	s_nop 1
	v_permlane16_swap_b32_e32 v50, v51
	v_add_f32_e32 v50, v50, v51
	v_mov_b32_e32 v51, v50
	s_nop 1
	v_permlane32_swap_b32_e32 v50, v51
	s_and_saveexec_b64 s[2:3], vcc
	v_add_f32_e32 v50, v50, v51
	ds_write_b32 v114, v50 offset:2048
	s_or_b64 exec, exec, s[2:3]
	s_mov_b64 s[2:3], 0x24000
	v_readlane_b32 s36, v247, 2
	v_lshl_add_u64 v[58:59], v[66:67], 0, s[2:3]
	v_readlane_b32 s37, v247, 3
	v_readlane_b32 s2, v247, 49
	v_readlane_b32 s3, v247, 50
	v_lshl_add_u64 v[60:61], v[58:59], 2, s[36:37]
	global_load_dwordx4 v[50:53], v[60:61], off nt
	global_load_dwordx4 v[54:57], v[60:61], off offset:16 nt
	v_lshlrev_b64 v[58:59], 1, v[58:59]
	v_lshl_add_u64 v[62:63], s[2:3], 0, v[58:59]
	v_or_b32_e32 v58, 0x100, v58
	v_readlane_b32 s38, v247, 4
	v_readlane_b32 s39, v247, 5
	v_readlane_b32 s40, v247, 6
	v_readlane_b32 s41, v247, 7
	v_readlane_b32 s42, v247, 8
	v_readlane_b32 s43, v247, 9
	v_readlane_b32 s44, v247, 10
	v_readlane_b32 s45, v247, 11
	v_readlane_b32 s46, v247, 12
	v_readlane_b32 s47, v247, 13
	v_readlane_b32 s48, v247, 14
	v_readlane_b32 s49, v247, 15
	v_readlane_b32 s50, v247, 16
	v_readlane_b32 s51, v247, 17
	s_waitcnt vmcnt(1)
	v_pk_add_f32 v[48:49], v[48:49], v[52:53]
	v_pk_add_f32 v[46:47], v[46:47], v[50:51]
	s_waitcnt vmcnt(0)
	v_pk_add_f32 v[50:51], v[44:45], v[56:57]
	v_pk_add_f32 v[44:45], v[42:43], v[54:55]
	v_cvt_pk_bf16_f32 v42, v46, v47
	v_cvt_pk_bf16_f32 v43, v48, v49
	v_cvt_pk_bf16_f32 v44, v44, v45
	v_cvt_pk_bf16_f32 v45, v50, v51
	global_store_dwordx4 v[62:63], v[42:45], off
	global_load_dwordx4 v[46:49], v[60:61], off offset:512 nt
	global_load_dwordx4 v[50:53], v[60:61], off offset:528 nt
	v_lshl_add_u64 v[54:55], s[2:3], 0, v[58:59]
	v_lshlrev_b32_e32 v56, 16, v42
	v_and_b32_e32 v42, 0xffff0000, v42
	v_lshlrev_b32_e32 v57, 16, v43
	v_and_b32_e32 v43, 0xffff0000, v43
	v_lshlrev_b32_e32 v58, 16, v44
	v_and_b32_e32 v44, 0xffff0000, v44
	v_lshlrev_b32_e32 v59, 16, v45
	v_and_b32_e32 v45, 0xffff0000, v45
	v_mul_f32_e32 v42, v42, v42
	v_mul_f32_e32 v43, v43, v43
	v_mul_f32_e32 v44, v44, v44
	v_mul_f32_e32 v45, v45, v45
	v_fmac_f32_e32 v42, v56, v56
	v_fmac_f32_e32 v43, v57, v57
	v_fmac_f32_e32 v44, v58, v58
	v_fmac_f32_e32 v45, v59, v59
	v_add_f32_e32 v42, v42, v43
	v_add_f32_e32 v43, v44, v45
	v_add_f32_e32 v44, v42, v43
	s_waitcnt vmcnt(1)
	v_pk_add_f32 v[40:41], v[40:41], v[48:49]
	v_pk_add_f32 v[38:39], v[38:39], v[46:47]
	s_waitcnt vmcnt(0)
	v_pk_add_f32 v[42:43], v[36:37], v[52:53]
	v_pk_add_f32 v[36:37], v[34:35], v[50:51]
	v_cvt_pk_bf16_f32 v34, v38, v39
	v_cvt_pk_bf16_f32 v35, v40, v41
	v_cvt_pk_bf16_f32 v36, v36, v37
	v_cvt_pk_bf16_f32 v37, v42, v43
	global_store_dwordx4 v[54:55], v[34:37], off
	v_lshlrev_b32_e32 v38, 16, v34
	v_lshlrev_b32_e32 v39, 16, v35
	v_and_b32_e32 v34, 0xffff0000, v34
	v_and_b32_e32 v35, 0xffff0000, v35
	v_lshlrev_b32_e32 v40, 16, v36
	v_and_b32_e32 v36, 0xffff0000, v36
	v_lshlrev_b32_e32 v41, 16, v37
	v_and_b32_e32 v37, 0xffff0000, v37
	v_mul_f32_e32 v34, v34, v34
	v_mul_f32_e32 v35, v35, v35
	v_mul_f32_e32 v36, v36, v36
	v_mul_f32_e32 v37, v37, v37
	v_fmac_f32_e32 v34, v38, v38
	v_fmac_f32_e32 v35, v39, v39
	v_fmac_f32_e32 v36, v40, v40
	v_fmac_f32_e32 v37, v41, v41
	v_add_f32_e32 v34, v34, v35
	v_add_f32_e32 v35, v36, v37
	v_add_f32_e32 v34, v34, v35
	v_add_f32_e32 v34, v44, v34
	v_mov_b32_e32 v35, v34
	s_nop 1
	v_permlane16_swap_b32_e32 v34, v35
	v_add_f32_e32 v34, v34, v35
	v_mov_b32_e32 v35, v34
	s_nop 1
	v_permlane32_swap_b32_e32 v34, v35
	s_and_saveexec_b64 s[2:3], vcc
	v_add_f32_e32 v34, v34, v35
	ds_write_b32 v114, v34 offset:2304
	s_or_b64 exec, exec, s[2:3]
	v_lshlrev_b64 v[34:35], 10, v[132:133]
	v_lshl_add_u64 v[34:35], v[34:35], 0, v[130:131]
	s_mov_b64 s[2:3], 0x28000
	v_readlane_b32 s36, v247, 2
	v_lshl_add_u64 v[44:45], v[34:35], 0, s[2:3]
	v_readlane_b32 s37, v247, 3
	v_readlane_b32 s2, v247, 49
	v_readlane_b32 s3, v247, 50
	v_lshl_add_u64 v[46:47], v[44:45], 2, s[36:37]
	global_load_dwordx4 v[36:39], v[46:47], off nt
	global_load_dwordx4 v[40:43], v[46:47], off offset:16 nt
	v_lshlrev_b64 v[44:45], 1, v[44:45]
	v_lshl_add_u64 v[48:49], s[2:3], 0, v[44:45]
	v_or_b32_e32 v44, 0x100, v44
	v_readlane_b32 s38, v247, 4
	v_readlane_b32 s39, v247, 5
	v_readlane_b32 s40, v247, 6
	v_readlane_b32 s41, v247, 7
	v_readlane_b32 s42, v247, 8
	v_readlane_b32 s43, v247, 9
	v_readlane_b32 s44, v247, 10
	v_readlane_b32 s45, v247, 11
	v_readlane_b32 s46, v247, 12
	v_readlane_b32 s47, v247, 13
	v_readlane_b32 s48, v247, 14
	v_readlane_b32 s49, v247, 15
	v_readlane_b32 s50, v247, 16
	v_readlane_b32 s51, v247, 17
	s_waitcnt vmcnt(1)
; __device__ __forceinline__ float bflo(unsigned w) { return __uint_as_float(w << 16); }
; __device__ __forceinline__ float bfhi(unsigned w) { return __uint_as_float(w & 0xffff0000u); }
; #define PG8_LAS __attribute__((address_space(3)))
; __device__ __forceinline__ unsigned cvt_pk_bf16(float lo, float hi) { f32x2c v = {lo, hi}; bf16x2c b = __builtin_convertvector(v, bf16x2c); return __builtin_bit_cast(unsigned, b); }
; __device__ __forceinline__ float bflo(unsigned w) { return __uint_as_float(w << 16); }
; __device__ __forceinline__ float bfhi(unsigned w) { return __uint_as_float(w & 0xffff0000u); }
; __device__ __forceinline__ float xsum16(float v) { auto r = __builtin_amdgcn_permlane16_swap(__float_as_uint(v), __float_as_uint(v), false, false); return __uint_as_float(r[0]) + __uint_as_float(r[1]); }
;     __device__ __forceinline__ void fused(const acc_t& acc, const Unit& u, int wr, int wc, int fr, int fq, PG8_LAS unsigned char* lds, int, int) const {
;     ...
;             for (int m = 0; m < 4; ++m) { const int row = row0 + ai * HALF + m * 16; const size_t off = (size_t)row * D + col0; float ss = 0.f;
; #pragma unroll
;                 for (int bj = 0; bj < 2; ++bj) { const size_t o = off + bj * HALF;
;                     const f32x4 r0 = *(const f32x4*)(x + o) + acc[ai][bj][m][0], r1 = *(const f32x4*)(x + o + 4) + acc[ai][bj][m][1];
;                     u32x4 w; w.x = cvt_pk_bf16(r0[0], r0[1]); w.y = cvt_pk_bf16(r0[2], r0[3]); w.z = cvt_pk_bf16(r1[0], r1[1]); w.w = cvt_pk_bf16(r1[2], r1[3]); *(u32x4*)(A2 + o) = w;
;                     const float q0 = bflo(w.x), q1 = bfhi(w.x), q2 = bflo(w.y), q3 = bfhi(w.y), q4 = bflo(w.z), q5 = bfhi(w.z), q6 = bflo(w.w), q7 = bfhi(w.w);
;                     ss += ((q0 * q0 + q1 * q1) + (q2 * q2 + q3 * q3)) + ((q4 * q4 + q5 * q5) + (q6 * q6 + q7 * q7)); }
;                 ss = xsum16(ss); ss = xsum32(ss);
;                 if (fq == 0) red[(ai * HALF + wr * 64 + m * 16 + fr) * 4 + wc] = ss;
;                 if (m & 1) asm volatile("" ::: "memory"); }
;         __syncthreads();
;         if (threadIdx.x < 256) { const f32x4 p = *(const PG8_LAS f32x4*)(red + threadIdx.x * 4); ssq[(size_t)(u.pm * BM + threadIdx.x) * 4 + u.pn] = (p.x + p.y) + (p.z + p.w); }
	v_pk_add_f32 v[32:33], v[32:33], v[38:39]
	v_pk_add_f32 v[30:31], v[30:31], v[36:37]
	s_waitcnt vmcnt(0)
	v_pk_add_f32 v[36:37], v[28:29], v[42:43]
	v_pk_add_f32 v[28:29], v[26:27], v[40:41]
	v_cvt_pk_bf16_f32 v26, v30, v31
	v_cvt_pk_bf16_f32 v27, v32, v33
	v_cvt_pk_bf16_f32 v28, v28, v29
	v_cvt_pk_bf16_f32 v29, v36, v37
	global_store_dwordx4 v[48:49], v[26:29], off
	global_load_dwordx4 v[30:33], v[46:47], off offset:512 nt
	global_load_dwordx4 v[36:39], v[46:47], off offset:528 nt
	v_lshl_add_u64 v[40:41], s[2:3], 0, v[44:45]
	v_lshlrev_b32_e32 v42, 16, v26
	v_and_b32_e32 v26, 0xffff0000, v26
	v_lshlrev_b32_e32 v43, 16, v27
	v_and_b32_e32 v27, 0xffff0000, v27
	v_lshlrev_b32_e32 v44, 16, v28
	v_and_b32_e32 v28, 0xffff0000, v28
	v_lshlrev_b32_e32 v45, 16, v29
	v_and_b32_e32 v29, 0xffff0000, v29
	v_mul_f32_e32 v26, v26, v26
	v_mul_f32_e32 v27, v27, v27
	v_mul_f32_e32 v28, v28, v28
	v_mul_f32_e32 v29, v29, v29
	v_fmac_f32_e32 v26, v42, v42
	v_fmac_f32_e32 v27, v43, v43
	v_fmac_f32_e32 v28, v44, v44
	v_fmac_f32_e32 v29, v45, v45
	v_add_f32_e32 v26, v26, v27
	v_add_f32_e32 v27, v28, v29
	v_add_f32_e32 v28, v26, v27
	s_waitcnt vmcnt(1)
	v_pk_add_f32 v[24:25], v[24:25], v[32:33]
	v_pk_add_f32 v[22:23], v[22:23], v[30:31]
	s_waitcnt vmcnt(0)
	v_pk_add_f32 v[26:27], v[20:21], v[38:39]
	v_pk_add_f32 v[20:21], v[18:19], v[36:37]
	v_cvt_pk_bf16_f32 v18, v22, v23
	v_cvt_pk_bf16_f32 v19, v24, v25
	v_cvt_pk_bf16_f32 v20, v20, v21
	v_cvt_pk_bf16_f32 v21, v26, v27
	global_store_dwordx4 v[40:41], v[18:21], off
	v_lshlrev_b32_e32 v22, 16, v18
	v_lshlrev_b32_e32 v23, 16, v19
	v_and_b32_e32 v18, 0xffff0000, v18
	v_and_b32_e32 v19, 0xffff0000, v19
	v_lshlrev_b32_e32 v24, 16, v20
	v_and_b32_e32 v20, 0xffff0000, v20
	v_lshlrev_b32_e32 v25, 16, v21
	v_and_b32_e32 v21, 0xffff0000, v21
	v_mul_f32_e32 v18, v18, v18
	v_mul_f32_e32 v19, v19, v19
	v_mul_f32_e32 v20, v20, v20
	v_mul_f32_e32 v21, v21, v21
	v_fmac_f32_e32 v18, v22, v22
	v_fmac_f32_e32 v19, v23, v23
	v_fmac_f32_e32 v20, v24, v24
	v_fmac_f32_e32 v21, v25, v25
	v_add_f32_e32 v18, v18, v19
	v_add_f32_e32 v19, v20, v21
	v_add_f32_e32 v18, v18, v19
	v_add_f32_e32 v18, v28, v18
	v_mov_b32_e32 v19, v18
	s_nop 1
	v_permlane16_swap_b32_e32 v18, v19
	v_add_f32_e32 v18, v18, v19
	v_mov_b32_e32 v19, v18
	s_nop 1
	v_permlane32_swap_b32_e32 v18, v19
	s_and_saveexec_b64 s[2:3], vcc
	v_add_f32_e32 v18, v18, v19
	ds_write_b32 v114, v18 offset:2560
	s_or_b64 exec, exec, s[2:3]
	s_mov_b64 s[2:3], 0x2c000
	v_readlane_b32 s36, v247, 2
	v_lshl_add_u64 v[26:27], v[34:35], 0, s[2:3]
	v_readlane_b32 s37, v247, 3
	v_readlane_b32 s2, v247, 49
	v_readlane_b32 s3, v247, 50
	v_lshl_add_u64 v[28:29], v[26:27], 2, s[36:37]
	global_load_dwordx4 v[18:21], v[28:29], off nt
	global_load_dwordx4 v[22:25], v[28:29], off offset:16 nt
	v_lshlrev_b64 v[26:27], 1, v[26:27]
	v_lshl_add_u64 v[30:31], s[2:3], 0, v[26:27]
	v_or_b32_e32 v26, 0x100, v26
	v_readlane_b32 s38, v247, 4
	v_readlane_b32 s39, v247, 5
	v_readlane_b32 s40, v247, 6
	v_readlane_b32 s41, v247, 7
	v_readlane_b32 s42, v247, 8
	v_readlane_b32 s43, v247, 9
	v_readlane_b32 s44, v247, 10
	v_readlane_b32 s45, v247, 11
	v_readlane_b32 s46, v247, 12
	v_readlane_b32 s47, v247, 13
	v_readlane_b32 s48, v247, 14
	v_readlane_b32 s49, v247, 15
	v_readlane_b32 s50, v247, 16
	v_readlane_b32 s51, v247, 17
	s_waitcnt vmcnt(1)
	v_pk_add_f32 v[16:17], v[16:17], v[20:21]
	v_pk_add_f32 v[14:15], v[14:15], v[18:19]
	s_waitcnt vmcnt(0)
	v_pk_add_f32 v[18:19], v[12:13], v[24:25]
	v_pk_add_f32 v[12:13], v[10:11], v[22:23]
	v_cvt_pk_bf16_f32 v10, v14, v15
	v_cvt_pk_bf16_f32 v11, v16, v17
	v_cvt_pk_bf16_f32 v12, v12, v13
	v_cvt_pk_bf16_f32 v13, v18, v19
	global_store_dwordx4 v[30:31], v[10:13], off
	global_load_dwordx4 v[14:17], v[28:29], off offset:512 nt
	global_load_dwordx4 v[18:21], v[28:29], off offset:528 nt
	v_lshl_add_u64 v[22:23], s[2:3], 0, v[26:27]
	v_lshlrev_b32_e32 v24, 16, v10
	v_and_b32_e32 v10, 0xffff0000, v10
	v_lshlrev_b32_e32 v25, 16, v11
	v_and_b32_e32 v11, 0xffff0000, v11
	v_lshlrev_b32_e32 v26, 16, v12
	v_and_b32_e32 v12, 0xffff0000, v12
	v_lshlrev_b32_e32 v27, 16, v13
	v_and_b32_e32 v13, 0xffff0000, v13
	v_mul_f32_e32 v10, v10, v10
	v_mul_f32_e32 v11, v11, v11
	v_mul_f32_e32 v12, v12, v12
	v_mul_f32_e32 v13, v13, v13
	v_fmac_f32_e32 v10, v24, v24
	v_fmac_f32_e32 v11, v25, v25
	v_fmac_f32_e32 v12, v26, v26
	v_fmac_f32_e32 v13, v27, v27
	v_add_f32_e32 v10, v10, v11
	v_add_f32_e32 v11, v12, v13
	v_add_f32_e32 v12, v10, v11
	s_waitcnt vmcnt(1)
	v_pk_add_f32 v[8:9], v[8:9], v[16:17]
	v_pk_add_f32 v[6:7], v[6:7], v[14:15]
	s_waitcnt vmcnt(0)
	v_pk_add_f32 v[10:11], v[4:5], v[20:21]
	v_pk_add_f32 v[4:5], v[2:3], v[18:19]
	v_cvt_pk_bf16_f32 v2, v6, v7
	v_cvt_pk_bf16_f32 v3, v8, v9
	v_cvt_pk_bf16_f32 v4, v4, v5
	v_cvt_pk_bf16_f32 v5, v10, v11
	global_store_dwordx4 v[22:23], v[2:5], off
	v_lshlrev_b32_e32 v6, 16, v2
	v_lshlrev_b32_e32 v7, 16, v3
	v_and_b32_e32 v2, 0xffff0000, v2
	v_and_b32_e32 v3, 0xffff0000, v3
	v_lshlrev_b32_e32 v8, 16, v4
	v_and_b32_e32 v4, 0xffff0000, v4
	v_lshlrev_b32_e32 v9, 16, v5
	v_and_b32_e32 v5, 0xffff0000, v5
	v_mul_f32_e32 v2, v2, v2
	v_mul_f32_e32 v3, v3, v3
	v_mul_f32_e32 v4, v4, v4
	v_mul_f32_e32 v5, v5, v5
	v_fmac_f32_e32 v2, v6, v6
	v_fmac_f32_e32 v3, v7, v7
	v_fmac_f32_e32 v4, v8, v8
	v_fmac_f32_e32 v5, v9, v9
	v_add_f32_e32 v2, v2, v3
	v_add_f32_e32 v3, v4, v5
	v_add_f32_e32 v2, v2, v3
	v_add_f32_e32 v2, v12, v2
	v_mov_b32_e32 v3, v2
	s_nop 1
	v_permlane16_swap_b32_e32 v2, v3
	v_add_f32_e32 v2, v2, v3
	v_mov_b32_e32 v3, v2
	s_nop 1
	v_permlane32_swap_b32_e32 v2, v3
	s_and_saveexec_b64 s[2:3], vcc
	v_add_f32_e32 v2, v2, v3
	ds_write_b32 v114, v2 offset:2816
	s_or_b64 exec, exec, s[2:3]
	s_movk_i32 s2, 0x100
	v_cmp_gt_u32_e32 vcc, s2, v0
	s_waitcnt lgkmcnt(0)
	s_barrier
	s_and_saveexec_b64 s[2:3], vcc
	s_cbranch_execz .LBB0_822
	v_add_u32_e32 v1, 0, v1
	ds_read_b128 v[2:5], v1
	v_or_b32_e32 v6, s1, v0
	v_mov_b32_e32 v7, 0
	s_ashr_i32 s1, s0, 31
	s_waitcnt lgkmcnt(0)
	v_mov_b32_e32 v8, v3
	v_mov_b32_e32 v9, v4
	v_mov_b32_e32 v3, v5
	v_pk_add_f32 v[2:3], v[8:9], v[2:3]
	s_nop 0
	v_add_f32_e32 v1, v2, v3
	v_lshl_add_u64 v[2:3], v[6:7], 4, s[8:9]
	v_lshl_add_u64 v[2:3], s[0:1], 2, v[2:3]
	global_store_dword v[2:3], v1, off
